# dense softmax: common path skips rescale math when running max is within threshold; phase-0 silu prologue loads batched
# speedup vs baseline: 1.0107x; 1.0107x over previous
; __device__ __forceinline__ int TID() { int t = threadIdx.x; asm volatile("" : "+v"(t)); return t; }
; __device__ __forceinline__ int v_rd_base(int lane) { return ((lane & 3) << 3) | (((lane >> 2) & 3) << 6) | (((lane >> 4) & 1) << 5) | (((lane >> 5) & 1) << 8); }
; #define SWAIT() do { if constexpr (SDEPTH == 2) asm volatile("s_waitcnt vmcnt(4)" ::: "memory"); else asm volatile("s_waitcnt vmcnt(0)" ::: "memory"); } while (0)
; #define ROW0(t) tile_row0<MODE>(u, (t))
; template <int MODE, int SDEPTH>
; __device__ __forceinline__ void attn_unit(const UnitP& u, char* lds) {
;   const int tid = TID(), wid = tid >> 6, lane = tid & 63, r32 = lane & 31, hi = lane >> 5;
;   bf16_t* V_lds = (bf16_t*)lds; bf16_t* K_lds = (bf16_t*)(lds + 2 * SHM_V);
;   float* ws = (float*)(lds + 2 * SHM_V + 2 * SHM_K) + wid * 64; float* li_l = ws; float* al_l = ws + 32;
;   const float* biasL = (const float*)(lds + BIAS_OFF);
;   const bf16_t* __restrict__ Kh = u.K; const bf16_t* __restrict__ Vh = u.V; const int LDK = u.ldk;
;   float m_reg = -1e30f, l_reg = 0; f32x16 o[4] = {}; bf16x8 qr[8];
;   const bf16_t* Qw = u.Q + (long)(wid * QBLK + r32) * u.ldq + hi * 8;
; #pragma unroll
;   for (int d0 = 0; d0 < 8; ++d0) qr[d0] = *reinterpret_cast<const bf16x8*>(Qw + d0 * 16);
;   const int vb0 = (int)(uintptr_t)V_lds + v_rd_base(lane);
;   struct { bf16x8 vs0, vs1, ks0, ks1; } sr_[SDEPTH];
;     ...
;   f32x16 pA0, pA1, pB0, pB1; float mnA, mnB, alA, alB; bf16x8 pa0, pa1, pa2, pa3; const int NT = u.NT;
;   constexpr int SE = 0, SO = SDEPTH - 1;
;   SLOAD(SE, ROW0(0)); asm volatile("s_waitcnt vmcnt(0)" ::: "memory"); SWRITE(0, SE); __syncthreads();
;   qkt(pA0, pA1, K_lds, qr, r32, hi); mask_tile<MODE>(pA0, pA1, u, 0, wid, r32, hi, biasL); partialSM(pA0, pA1, m_reg, mnA, alA);
;   SLOAD(SO, ROW0(1)); if constexpr (SDEPTH == 2) { if (2 < NT) SLOAD(SE, ROW0(2)); }
;   SWAIT(); SWRITE(1, SO); __syncthreads();
.LBB0_528:
	s_andn2_b64 vcc, exec, s[8:9]
	s_mov_b64 s[8:9], -1
	s_cbranch_vccnz .LBB0_524
	s_lshl_b32 s2, s12, 8
	s_and_b32 s29, s2, 0x1f00
	s_and_b32 s13, s12, 0xffffff80
	s_mul_i32 s2, s29, 0x1800
	s_add_u32 s10, s19, s2
	s_addc_u32 s11, s20, 0
	s_lshl_b32 s2, s12, 2
	s_and_b32 s2, s2, 0xffffff80
	s_ashr_i32 s3, s2, 31
	s_lshl_b64 s[8:9], s[2:3], 1
	s_add_u32 s2, s10, s8
	s_addc_u32 s3, s11, s9
	s_add_i32 s10, s13, 0x800
	s_ashr_i32 s11, s10, 31
	s_lshl_b64 s[10:11], s[10:11], 1
	s_add_u32 s14, s19, s10
	s_addc_u32 s15, s20, s11
	s_add_i32 s12, s13, 0xa00
	s_ashr_i32 s13, s12, 31
	s_lshl_b64 s[12:13], s[12:13], 1
	v_mov_b32_e32 v48, v216
	s_add_u32 s16, s19, s12
	s_addc_u32 s17, s20, s13
	v_ashrrev_i32_e32 v195, 6, v48
	v_and_b32_e32 v193, 31, v48
	v_and_b32_e32 v0, 0x3fffffc0, v48
	s_add_i32 s34, 0, 0x10000
	v_lshlrev_b32_e32 v98, 5, v195
	v_bfe_u32 v194, v48, 5, 1
	v_lshl_add_u32 v99, v0, 2, s34
	v_or_b32_e32 v2, v98, v193
	v_mov_b64_e32 v[0:1], s[2:3]
	s_movk_i32 s36, 0x1800
	v_mad_i64_i32 v[0:1], s[2:3], v2, s36, v[0:1]
	v_lshlrev_b32_e32 v96, 4, v194
	v_and_b32_e32 v101, 63, v48
	v_lshl_add_u64 v[0:1], v[0:1], 0, v[96:97]
	v_lshlrev_b32_e32 v192, 4, v48
	global_load_dwordx4 v[130:133], v[0:1], off
	global_load_dwordx4 v[126:129], v[0:1], off offset:32
	global_load_dwordx4 v[122:125], v[0:1], off offset:64
	global_load_dwordx4 v[118:121], v[0:1], off offset:96
	global_load_dwordx4 v[114:117], v[0:1], off offset:128
	global_load_dwordx4 v[110:113], v[0:1], off offset:160
	global_load_dwordx4 v[106:109], v[0:1], off offset:192
	global_load_dwordx4 v[102:105], v[0:1], off offset:224
	v_lshlrev_b32_e32 v99, 8, v195
	v_add_u32_e32 v99, 0x22000, v99
	v_lshl_add_u32 v199, v193, 2, v99
	v_cmp_gt_u32_e64 s[40:41], 32, v101
	v_lshlrev_b32_e32 v0, 3, v101
	v_and_b32_e32 v1, 0xc0, v192
	v_lshlrev_b32_e32 v2, 1, v48
	v_and_or_b32 v1, v0, 24, v1
	v_and_b32_e32 v2, 32, v2
	v_and_b32_e32 v0, 0x100, v0
	v_or3_b32 v196, v1, v2, v0
	v_ashrrev_i32_e32 v50, 4, v48
	v_lshlrev_b32_e32 v16, 3, v48
	v_and_b32_e32 v51, 0x78, v16
	v_and_b32_e32 v3, 15, v48
	v_lshlrev_b32_e32 v3, 4, v3
	s_movk_i32 s2, 0x1800
	v_mad_u32_u24 v184, v50, s2, v3
	s_add_u32 s2, s16, 0x30000
	s_addc_u32 s3, s17, 0
	s_add_u32 s10, s14, 0x30000
	s_addc_u32 s11, s15, 0
	global_load_dwordx4 v[134:137], v184, s[16:17]
	global_load_dwordx4 v[138:141], v184, s[2:3]
	global_load_dwordx4 v[142:145], v184, s[14:15]
	global_load_dwordx4 v[146:149], v184, s[10:11]
	s_add_u32 s16, s16, 0x60000
	s_addc_u32 s17, s17, 0
	s_add_u32 s2, s2, 0x60000
	s_addc_u32 s3, s3, 0
	s_add_u32 s14, s14, 0x60000
	s_addc_u32 s15, s15, 0
	s_add_u32 s10, s10, 0x60000
	s_addc_u32 s11, s11, 0
	global_load_dwordx4 v[150:153], v184, s[16:17]
	global_load_dwordx4 v[154:157], v184, s[2:3]
	global_load_dwordx4 v[158:161], v184, s[14:15]
	global_load_dwordx4 v[162:165], v184, s[10:11]
	s_add_u32 s16, s16, 0x60000
	s_addc_u32 s17, s17, 0
	s_add_u32 s2, s2, 0x60000
	s_addc_u32 s3, s3, 0
	s_add_u32 s14, s14, 0x60000
	s_addc_u32 s15, s15, 0
	s_add_u32 s10, s10, 0x60000
	s_addc_u32 s11, s11, 0
	v_and_b32_e32 v18, 0xfffff0, v50
	v_lshlrev_b32_e32 v19, 1, v50
	v_and_or_b32 v18, v19, 8, v18
	v_lshrrev_b32_e32 v19, 1, v50
	v_lshrrev_b32_e32 v18, 1, v18
	v_bfe_u32 v16, v16, 5, 2
	v_and_b32_e32 v20, 3, v50
	v_or_b32_e32 v18, v18, v16
	v_and_or_b32 v19, v19, 4, v20
	v_lshlrev_b32_e32 v20, 1, v51
	v_lshlrev_b32_e32 v18, 9, v18
	v_lshlrev_b32_e32 v19, 6, v19
	v_and_b32_e32 v21, 48, v20
	v_or3_b32 v197, v18, v19, v21
	v_lshlrev_b32_e32 v4, 8, v50
	v_and_b32_e32 v5, 0xf0, v48
	v_bitop3_b32 v4, v20, v4, v5 bitop3:0xde
	v_add_u32_e32 v185, 0x10000, v4
	v_lshlrev_b32_e32 v60, 8, v193
	v_and_b32_e32 v61, 0xf0, v192
	v_bitop3_b32 v52, v96, v60, v61 bitop3:0xde
	v_add_u32_e32 v204, 0x10000, v52
	v_or_b32_e32 v52, 32, v96
	v_bitop3_b32 v52, v52, v60, v61 bitop3:0xde
	v_add_u32_e32 v205, 0x10000, v52
	v_or_b32_e32 v52, 64, v96
	v_bitop3_b32 v52, v52, v60, v61 bitop3:0xde
	v_add_u32_e32 v206, 0x10000, v52
	v_or_b32_e32 v52, 96, v96
	v_bitop3_b32 v52, v52, v60, v61 bitop3:0xde
	v_add_u32_e32 v207, 0x10000, v52
	v_or_b32_e32 v52, 128, v96
	v_bitop3_b32 v52, v52, v60, v61 bitop3:0xde
	v_add_u32_e32 v208, 0x10000, v52
	v_or_b32_e32 v52, 160, v96
	v_bitop3_b32 v52, v52, v60, v61 bitop3:0xde
	v_add_u32_e32 v209, 0x10000, v52
	v_or_b32_e32 v52, 192, v96
	v_bitop3_b32 v52, v52, v60, v61 bitop3:0xde
	v_add_u32_e32 v210, 0x10000, v52
	v_or_b32_e32 v52, 224, v96
	v_bitop3_b32 v52, v52, v60, v61 bitop3:0xde
	v_add_u32_e32 v211, 0x10000, v52
	v_mov_b32_e32 v174, v224
	v_mov_b32_e32 v175, 0
	v_mul_f32_e32 v214, 0xbe0293ee, v174
	s_mov_b32 s31, 0
	v_readfirstlane_b32 s36, v195
	s_waitcnt vmcnt(4)
; __device__ __forceinline__ int v_rd_base(int lane) { return ((lane & 3) << 3) | (((lane >> 2) & 3) << 6) | (((lane >> 4) & 1) << 5) | (((lane >> 5) & 1) << 8); }
; #define SWAIT() do { if constexpr (SDEPTH == 2) asm volatile("s_waitcnt vmcnt(4)" ::: "memory"); else asm volatile("s_waitcnt vmcnt(0)" ::: "memory"); } while (0)
; #define ROW0(t) tile_row0<MODE>(u, (t))
; template <int MODE, int SDEPTH>
; __device__ __forceinline__ void attn_unit(const UnitP& u, char* lds) {
;     ...
;   float m_reg = -1e30f, l_reg = 0; f32x16 o[4] = {}; bf16x8 qr[8];
;   const bf16_t* Qw = u.Q + (long)(wid * QBLK + r32) * u.ldq + hi * 8;
; #pragma unroll
;   for (int d0 = 0; d0 < 8; ++d0) qr[d0] = *reinterpret_cast<const bf16x8*>(Qw + d0 * 16);
;   const int vb0 = (int)(uintptr_t)V_lds + v_rd_base(lane);
;   struct { bf16x8 vs0, vs1, ks0, ks1; } sr_[SDEPTH];
;     ...
;   f32x16 pA0, pA1, pB0, pB1; float mnA, mnB, alA, alB; bf16x8 pa0, pa1, pa2, pa3; const int NT = u.NT;
;   constexpr int SE = 0, SO = SDEPTH - 1;
;   SLOAD(SE, ROW0(0)); asm volatile("s_waitcnt vmcnt(0)" ::: "memory"); SWRITE(0, SE); __syncthreads();
;   qkt(pA0, pA1, K_lds, qr, r32, hi); mask_tile<MODE>(pA0, pA1, u, 0, wid, r32, hi, biasL); partialSM(pA0, pA1, m_reg, mnA, alA);
;   SLOAD(SO, ROW0(1)); if constexpr (SDEPTH == 2) { if (2 < NT) SLOAD(SE, ROW0(2)); }
;   SWAIT(); SWRITE(1, SO); __syncthreads();
	ds_write_b128 v197, v[134:137] offset:0
	ds_write_b128 v197, v[138:141] offset:8192
	ds_write_b128 v185, v[142:145] offset:0
	ds_write_b128 v185, v[146:149] offset:8192
	s_waitcnt vmcnt(0)
	ds_write_b128 v197, v[150:153] offset:16384
	ds_write_b128 v197, v[154:157] offset:24576
	ds_write_b128 v185, v[158:161] offset:16384
	ds_write_b128 v185, v[162:165] offset:24576
	s_nop 1
	global_load_dwordx4 v[134:137], v184, s[16:17]
	global_load_dwordx4 v[138:141], v184, s[2:3]
	global_load_dwordx4 v[142:145], v184, s[14:15]
	global_load_dwordx4 v[146:149], v184, s[10:11]
	s_add_u32 s16, s16, 0x60000
	s_addc_u32 s17, s17, 0
	s_add_u32 s2, s2, 0x60000
	s_addc_u32 s3, s3, 0
	s_add_u32 s14, s14, 0x60000
	s_addc_u32 s15, s15, 0
	s_add_u32 s10, s10, 0x60000
	s_addc_u32 s11, s11, 0
	global_load_dwordx4 v[186:189], v184, s[16:17]
	global_load_dwordx4 v[220:223], v184, s[2:3]
	global_load_dwordx4 v[246:249], v184, s[14:15]
	global_load_dwordx4 v[200:203], v184, s[10:11]
	s_add_u32 s16, s16, 0x60000
	s_addc_u32 s17, s17, 0
	s_add_u32 s2, s2, 0x60000
	s_addc_u32 s3, s3, 0
	s_add_u32 s14, s14, 0x60000
	s_addc_u32 s15, s15, 0
	s_add_u32 s10, s10, 0x60000
	s_addc_u32 s11, s11, 0
	v_mov_b32_e32 v0, 0
	v_mov_b32_e32 v1, 0
	v_mov_b32_e32 v2, 0
	v_mov_b32_e32 v3, 0
	v_mov_b32_e32 v4, 0
	v_mov_b32_e32 v5, 0
	v_mov_b32_e32 v6, 0
	v_mov_b32_e32 v7, 0
	v_mov_b32_e32 v8, 0
	v_mov_b32_e32 v9, 0
	v_mov_b32_e32 v10, 0
	v_mov_b32_e32 v11, 0
	v_mov_b32_e32 v12, 0
	v_mov_b32_e32 v13, 0
	v_mov_b32_e32 v14, 0
	v_mov_b32_e32 v15, 0
	v_mov_b32_e32 v48, 0
	v_mov_b32_e32 v49, 0
	v_mov_b32_e32 v50, 0
	v_mov_b32_e32 v51, 0
	v_mov_b32_e32 v52, 0
	v_mov_b32_e32 v53, 0
	v_mov_b32_e32 v54, 0
	v_mov_b32_e32 v55, 0
	v_mov_b32_e32 v56, 0
	v_mov_b32_e32 v57, 0
	v_mov_b32_e32 v58, 0
	v_mov_b32_e32 v59, 0
	v_mov_b32_e32 v60, 0
	v_mov_b32_e32 v61, 0
	v_mov_b32_e32 v62, 0
	v_mov_b32_e32 v63, 0
	v_mov_b32_e32 v32, 0
	v_mov_b32_e32 v33, 0
	v_mov_b32_e32 v34, 0
	v_mov_b32_e32 v35, 0
	v_mov_b32_e32 v36, 0
	v_mov_b32_e32 v37, 0
	v_mov_b32_e32 v38, 0
	v_mov_b32_e32 v39, 0
	v_mov_b32_e32 v40, 0
	v_mov_b32_e32 v41, 0
	v_mov_b32_e32 v42, 0
	v_mov_b32_e32 v43, 0
	v_mov_b32_e32 v44, 0
	v_mov_b32_e32 v45, 0
	v_mov_b32_e32 v46, 0
	v_mov_b32_e32 v47, 0
	v_mov_b32_e32 v16, 0
	v_mov_b32_e32 v17, 0
	v_mov_b32_e32 v18, 0
	v_mov_b32_e32 v19, 0
	v_mov_b32_e32 v20, 0
	v_mov_b32_e32 v21, 0
	v_mov_b32_e32 v22, 0
	v_mov_b32_e32 v23, 0
	v_mov_b32_e32 v24, 0
	v_mov_b32_e32 v25, 0
	v_mov_b32_e32 v26, 0
	v_mov_b32_e32 v27, 0
	v_mov_b32_e32 v28, 0
	v_mov_b32_e32 v29, 0
	v_mov_b32_e32 v30, 0
	v_mov_b32_e32 v31, 0
	s_waitcnt lgkmcnt(0)
	s_barrier
	ds_read_b128 v[150:153], v204 offset:0
	ds_read_b128 v[154:157], v204 offset:8192
	ds_read_b128 v[158:161], v205 offset:0
	ds_read_b128 v[162:165], v205 offset:8192
	ds_read_b128 v[228:231], v206 offset:0
	ds_read_b128 v[232:235], v206 offset:8192
	ds_read_b128 v[236:239], v207 offset:0
	ds_read_b128 v[240:243], v207 offset:8192
	s_cmp_lt_u32 s36, 4
	s_cbranch_scc1 .Lda_lead
	s_barrier

; __device__ __forceinline__ void partialSM(f32x16& p0, f32x16& p1, float& m_reg, float& mn, float& alpha) {
;   constexpr float C = SCALE * 1.4426950408889634f;
;   float pmax = p0[0];
; #pragma unroll
;   for (int r = 1; r < 16; ++r) pmax = fmaxf(pmax, p0[r]);
; #pragma unroll
;   for (int r = 0; r < 16; ++r) pmax = fmaxf(pmax, p1[r]);
;   { auto rr = __builtin_amdgcn_permlane32_swap(__float_as_uint(pmax), __float_as_uint(pmax), false, false);
;     pmax = fmaxf(__uint_as_float(rr[0]), __uint_as_float(rr[1])); }
;   if (__builtin_expect(__all(pmax - m_reg <= THR / SCALE), 1)) { mn = m_reg; alpha = 1.f; }
;   else { mn = fmaxf(m_reg, pmax); alpha = __builtin_amdgcn_exp2f((m_reg - mn) * C); m_reg = mn; }
;   float mnC = -mn * C;
; #pragma unroll
;   for (int r = 0; r < 16; ++r) p0[r] = fmaf(p0[r], C, mnC);
; #pragma unroll
;   for (int r = 0; r < 16; ++r) p1[r] = fmaf(p1[r], C, mnC);
; #pragma unroll
;   for (int r = 0; r < 16; ++r) p0[r] = __builtin_amdgcn_exp2f(p0[r]);
; }
; __device__ __forceinline__ void finishSM(f32x16& p0, f32x16& p1, float alpha, float& l_reg, bf16x8& pa0, bf16x8& pa1, bf16x8& pa2, bf16x8& pa3) {
; #pragma unroll
;   for (int r = 0; r < 16; ++r) p1[r] = __builtin_amdgcn_exp2f(p1[r]);
;   float ps = 0;
; #pragma unroll
;   for (int r = 0; r < 16; ++r) ps += p0[r];
; #pragma unroll
;   for (int r = 0; r < 16; ++r) ps += p1[r];
;   { auto rr = __builtin_amdgcn_permlane32_swap(__float_as_uint(ps), __float_as_uint(ps), false, false);
;     ps = __uint_as_float(rr[0]) + __uint_as_float(rr[1]); }
;   l_reg = l_reg * alpha + ps;
;     ...
;   PK4(p0, 0, pa0); PK4(p0, 8, pa1); PK4(p1, 0, pa2); PK4(p1, 8, pa3);
;     ...
; }
.Lda_y0:
	s_barrier
	v_max3_f32 v190, v80, v81, v82
	v_max3_f32 v191, v64, v65, v66
	v_max3_f32 v190, v190, v83, v84
	v_max3_f32 v191, v191, v67, v68
	v_max3_f32 v190, v190, v85, v86
	v_max3_f32 v191, v191, v69, v70
	v_max3_f32 v190, v190, v87, v88
	v_max3_f32 v191, v191, v71, v72
	v_max3_f32 v190, v190, v89, v90
	v_max3_f32 v191, v191, v73, v74
	v_max3_f32 v190, v190, v91, v92
	v_max3_f32 v191, v191, v75, v76
	v_max3_f32 v190, v190, v93, v94
	v_max3_f32 v191, v191, v77, v78
	v_max3_f32 v190, v190, v95, v79
	v_max_f32_e32 v190, v190, v191
	v_mov_b32_e32 v191, v190
	s_nop 1
	v_permlane32_swap_b32_e32 v190, v191
	s_nop 0
	v_max_f32_e32 v212, v190, v191
	v_sub_f32_e32 v190, v212, v174
	v_cmp_ge_f32_e32 vcc, s86, v190
	s_nop 3
	s_cmp_eq_u64 vcc, exec
	s_cbranch_scc1 .Lda_common_0
	v_max_f32_e32 v191, v174, v212
	v_sub_f32_e32 v215, v174, v191
	v_mul_f32_e32 v215, s92, v215
	v_exp_f32_e32 v213, v215
	v_mov_b32_e32 v174, v191
	v_mul_f32_e32 v214, 0xbe0293ee, v174
	v_mul_f32_e32 v175, v175, v213
	s_and_saveexec_b64 s[12:13], s[40:41]
	ds_write_b32 v199, v213 offset:128
	s_or_b64 exec, exec, s[12:13]
	s_waitcnt lgkmcnt(0)
	v_add_u32_e32 v215, v99, v96
	ds_read_b128 v[228:231], v215 offset:128
	ds_read_b128 v[232:235], v215 offset:160
	ds_read_b128 v[236:239], v215 offset:192
	ds_read_b128 v[240:243], v215 offset:224
	s_waitcnt lgkmcnt(0)
	v_pk_mul_f32 v[0:1], v[0:1], v[228:229]
	v_pk_mul_f32 v[2:3], v[2:3], v[230:231]
	v_pk_mul_f32 v[4:5], v[4:5], v[232:233]
	v_pk_mul_f32 v[6:7], v[6:7], v[234:235]
	v_pk_mul_f32 v[8:9], v[8:9], v[236:237]
	v_pk_mul_f32 v[10:11], v[10:11], v[238:239]
	v_pk_mul_f32 v[12:13], v[12:13], v[240:241]
	v_pk_mul_f32 v[14:15], v[14:15], v[242:243]
	v_pk_mul_f32 v[48:49], v[48:49], v[228:229]
	v_pk_mul_f32 v[50:51], v[50:51], v[230:231]
	v_pk_mul_f32 v[52:53], v[52:53], v[232:233]
	v_pk_mul_f32 v[54:55], v[54:55], v[234:235]
	v_pk_mul_f32 v[56:57], v[56:57], v[236:237]
	v_pk_mul_f32 v[58:59], v[58:59], v[238:239]
	v_pk_mul_f32 v[60:61], v[60:61], v[240:241]
	v_pk_mul_f32 v[62:63], v[62:63], v[242:243]
	v_pk_mul_f32 v[32:33], v[32:33], v[228:229]
	v_pk_mul_f32 v[34:35], v[34:35], v[230:231]
	v_pk_mul_f32 v[36:37], v[36:37], v[232:233]
	v_pk_mul_f32 v[38:39], v[38:39], v[234:235]
	v_pk_mul_f32 v[40:41], v[40:41], v[236:237]
	v_pk_mul_f32 v[42:43], v[42:43], v[238:239]
	v_pk_mul_f32 v[44:45], v[44:45], v[240:241]
	v_pk_mul_f32 v[46:47], v[46:47], v[242:243]
	v_pk_mul_f32 v[16:17], v[16:17], v[228:229]
	v_pk_mul_f32 v[18:19], v[18:19], v[230:231]
	v_pk_mul_f32 v[20:21], v[20:21], v[232:233]
	v_pk_mul_f32 v[22:23], v[22:23], v[234:235]
	v_pk_mul_f32 v[24:25], v[24:25], v[236:237]
	v_pk_mul_f32 v[26:27], v[26:27], v[238:239]
	v_pk_mul_f32 v[28:29], v[28:29], v[240:241]
	v_pk_mul_f32 v[30:31], v[30:31], v[242:243]
.Lda_common_0:
	v_fma_f32 v80, v80, s92, v214
	v_fma_f32 v81, v81, s92, v214
	v_fma_f32 v82, v82, s92, v214
	v_fma_f32 v83, v83, s92, v214
	v_fma_f32 v84, v84, s92, v214
	v_fma_f32 v85, v85, s92, v214
	v_fma_f32 v86, v86, s92, v214
	v_fma_f32 v87, v87, s92, v214
	v_fma_f32 v88, v88, s92, v214
	v_fma_f32 v89, v89, s92, v214
	v_fma_f32 v90, v90, s92, v214
	v_fma_f32 v91, v91, s92, v214
	v_fma_f32 v92, v92, s92, v214
	v_fma_f32 v93, v93, s92, v214
	v_fma_f32 v94, v94, s92, v214
	v_fma_f32 v95, v95, s92, v214
	v_fma_f32 v64, v64, s92, v214
	v_fma_f32 v65, v65, s92, v214
	v_fma_f32 v66, v66, s92, v214
	v_fma_f32 v67, v67, s92, v214
	v_fma_f32 v68, v68, s92, v214
	v_fma_f32 v69, v69, s92, v214
	v_fma_f32 v70, v70, s92, v214
	v_fma_f32 v71, v71, s92, v214
	v_fma_f32 v72, v72, s92, v214
	v_fma_f32 v73, v73, s92, v214
	v_fma_f32 v74, v74, s92, v214
	v_fma_f32 v75, v75, s92, v214
	v_fma_f32 v76, v76, s92, v214
	v_fma_f32 v77, v77, s92, v214
	v_fma_f32 v78, v78, s92, v214
	v_fma_f32 v79, v79, s92, v214
.Lda_noresc_0:
	v_exp_f32_e32 v80, v80
	v_exp_f32_e32 v81, v81
	v_exp_f32_e32 v82, v82
	v_exp_f32_e32 v83, v83
	v_exp_f32_e32 v84, v84
	v_exp_f32_e32 v85, v85
	v_exp_f32_e32 v86, v86
	v_exp_f32_e32 v87, v87
	v_exp_f32_e32 v88, v88
	v_exp_f32_e32 v89, v89
	v_exp_f32_e32 v90, v90
	v_exp_f32_e32 v91, v91
	v_exp_f32_e32 v92, v92
	v_exp_f32_e32 v93, v93
	v_exp_f32_e32 v94, v94
	v_exp_f32_e32 v95, v95
	v_exp_f32_e32 v64, v64
	v_exp_f32_e32 v65, v65
	v_exp_f32_e32 v66, v66
	v_exp_f32_e32 v67, v67
	v_exp_f32_e32 v68, v68
	v_exp_f32_e32 v69, v69
	v_exp_f32_e32 v70, v70
	v_exp_f32_e32 v71, v71
	v_exp_f32_e32 v72, v72
	v_exp_f32_e32 v73, v73
	v_exp_f32_e32 v74, v74
	v_exp_f32_e32 v75, v75
	v_exp_f32_e32 v76, v76
	v_exp_f32_e32 v77, v77
	v_exp_f32_e32 v78, v78
	v_exp_f32_e32 v79, v79
	v_add_f32_e32 v190, v80, v81
	v_add_f32_e32 v191, v82, v83
	v_add_f32_e32 v190, v190, v84
	v_add_f32_e32 v191, v191, v85
	v_add_f32_e32 v190, v190, v86
	v_add_f32_e32 v191, v191, v87
	v_add_f32_e32 v190, v190, v88
	v_add_f32_e32 v191, v191, v89
	v_add_f32_e32 v190, v190, v90
	v_add_f32_e32 v191, v191, v91
	v_add_f32_e32 v190, v190, v92
	v_add_f32_e32 v191, v191, v93
	v_add_f32_e32 v190, v190, v94
	v_add_f32_e32 v191, v191, v95
	v_add_f32_e32 v190, v190, v64
	v_add_f32_e32 v191, v191, v65
	v_add_f32_e32 v190, v190, v66
	v_add_f32_e32 v191, v191, v67
	v_add_f32_e32 v190, v190, v68
	v_add_f32_e32 v191, v191, v69
	v_add_f32_e32 v190, v190, v70
	v_add_f32_e32 v191, v191, v71
	v_add_f32_e32 v190, v190, v72
	v_add_f32_e32 v191, v191, v73
	v_add_f32_e32 v190, v190, v74
	v_add_f32_e32 v191, v191, v75
	v_add_f32_e32 v190, v190, v76
	v_add_f32_e32 v191, v191, v77
	v_add_f32_e32 v190, v190, v78
	v_add_f32_e32 v191, v191, v79
	v_add_f32_e32 v190, v190, v191
	v_mov_b32_e32 v191, v190
	v_cvt_pk_bf16_f32 v166, v80, v81
	v_cvt_pk_bf16_f32 v167, v82, v83
	v_cvt_pk_bf16_f32 v168, v84, v85
	v_cvt_pk_bf16_f32 v169, v86, v87
	v_cvt_pk_bf16_f32 v170, v88, v89
	v_cvt_pk_bf16_f32 v171, v90, v91
	v_cvt_pk_bf16_f32 v172, v92, v93
	v_cvt_pk_bf16_f32 v173, v94, v95
	v_cvt_pk_bf16_f32 v176, v64, v65
	v_cvt_pk_bf16_f32 v177, v66, v67
	v_cvt_pk_bf16_f32 v178, v68, v69
	v_cvt_pk_bf16_f32 v179, v70, v71
	v_cvt_pk_bf16_f32 v180, v72, v73
	v_cvt_pk_bf16_f32 v181, v74, v75
	v_cvt_pk_bf16_f32 v182, v76, v77
	v_cvt_pk_bf16_f32 v183, v78, v79
	s_nop 1
	v_permlane32_swap_b32_e32 v190, v191
	v_permlane32_swap_b32_e32 v166, v168
	v_permlane32_swap_b32_e32 v167, v169
	v_permlane32_swap_b32_e32 v170, v172
	v_permlane32_swap_b32_e32 v171, v173
	v_permlane32_swap_b32_e32 v176, v178
	v_permlane32_swap_b32_e32 v177, v179
	v_permlane32_swap_b32_e32 v180, v182
	v_permlane32_swap_b32_e32 v181, v183
	v_add_f32_e32 v190, v190, v191
	v_add_f32_e32 v175, v175, v190
	s_add_u32 s31, s31, 1
	s_cmp_lt_u32 s31, 132
	s_cbranch_scc0 .Lda_skipk_0
	ds_read_b128 v[150:153], v204 offset:16384
	ds_read_b128 v[154:157], v204 offset:24576
	ds_read_b128 v[158:161], v205 offset:16384
	ds_read_b128 v[162:165], v205 offset:24576
	ds_read_b128 v[228:231], v206 offset:16384
	ds_read_b128 v[232:235], v206 offset:24576
	ds_read_b128 v[236:239], v207 offset:16384
	ds_read_b128 v[240:243], v207 offset:24576
; #define SBAR() __builtin_amdgcn_sched_barrier(0)
; __device__ __forceinline__ void qkt(f32x16& p0, f32x16& p1, const bf16_t* Ks, const bf16x8* qr, int r32, int hi) {
;   p0 = f32x16{}; p1 = f32x16{};
; #pragma unroll
;   for (int d0 = 0; d0 < 8; ++d0) { int cb = (d0 * 16 + hi * 8) * 2;
;     bf16x8 b0 = *reinterpret_cast<const bf16x8*>((const char*)Ks + KSWZ(r32, cb));
;     bf16x8 b1 = *reinterpret_cast<const bf16x8*>((const char*)Ks + KSWZ(32 + r32, cb));
;     p0 = __builtin_amdgcn_mfma_f32_32x32x16_bf16(b0, qr[d0], p0, 0, 0, 0);
;     p1 = __builtin_amdgcn_mfma_f32_32x32x16_bf16(b1, qr[d0], p1, 0, 0, 0); }
; }
; __device__ __forceinline__ int v_st(int k, int c) { const int kk = (k & ~0xC) | ((k & 4) << 1) | ((k & 8) >> 1); return ((kk >> 3) * 4 + (c >> 5)) * 512 + ((kk & 7) * 32 + (c & 31)) * 2; }
; __device__ __forceinline__ int v_rd_base(int lane) { return ((lane & 3) << 3) | (((lane >> 2) & 3) << 6) | (((lane >> 4) & 1) << 5) | (((lane >> 5) & 1) << 8); }
; template <int OFF> __device__ __forceinline__ s16x4 tr_read(int vb) {
;   s16x4 r; asm volatile("ds_read_b64_tr_b16 %0, %1 offset:%2" : "=&v"(r) : "v"(vb), "i"(OFF) : "memory"); return r;
; }
; template <int D0> __device__ __forceinline__ void pv_one(f32x16& od, int vb, bf16x8 pa0, bf16x8 pa1, bf16x8 pa2, bf16x8 pa3) {
;   const s16x4 l0 = tr_read<v_rd_off(D0, 0, 0)>(vb), h0 = tr_read<v_rd_off(D0, 0, 1)>(vb), l1 = tr_read<v_rd_off(D0, 1, 0)>(vb), h1 = tr_read<v_rd_off(D0, 1, 1)>(vb);
;   const s16x4 l2 = tr_read<v_rd_off(D0, 2, 0)>(vb), h2 = tr_read<v_rd_off(D0, 2, 1)>(vb), l3 = tr_read<v_rd_off(D0, 3, 0)>(vb), h3 = tr_read<v_rd_off(D0, 3, 1)>(vb);
;   asm volatile("s_waitcnt lgkmcnt(0)" ::: "memory"); SBAR();
;     ...
;   od = __builtin_amdgcn_mfma_f32_32x32x16_bf16(pa0, PK(l0, h0), od, 0, 0, 0);
;   od = __builtin_amdgcn_mfma_f32_32x32x16_bf16(pa1, PK(l1, h1), od, 0, 0, 0);
;   od = __builtin_amdgcn_mfma_f32_32x32x16_bf16(pa2, PK(l2, h2), od, 0, 0, 0);
;   od = __builtin_amdgcn_mfma_f32_32x32x16_bf16(pa3, PK(l3, h3), od, 0, 0, 0);
;     ...
; }
; __device__ __forceinline__ void pv_d0(f32x16* o, int vb, bf16x8 pa0, bf16x8 pa1, bf16x8 pa2, bf16x8 pa3) {
;   pv_one<0>(o[0], vb, pa0, pa1, pa2, pa3); pv_one<1>(o[1], vb, pa0, pa1, pa2, pa3); pv_one<2>(o[2], vb, pa0, pa1, pa2, pa3); pv_one<3>(o[3], vb, pa0, pa1, pa2, pa3);
.Lda_skipk_0:
	s_barrier
	s_setprio 3
	s_waitcnt vmcnt(4)
	ds_write_b128 v197, v[186:189] offset:49152
	ds_write_b128 v197, v[220:223] offset:57344
	ds_write_b128 v185, v[246:249] offset:49152
	ds_write_b128 v185, v[200:203] offset:57344
	s_waitcnt lgkmcnt(10)
	v_mfma_f32_32x32x16_bf16 v[80:95], v[150:153], v[130:133], 0
	v_mfma_f32_32x32x16_bf16 v[64:79], v[154:157], v[130:133], 0
	global_load_dwordx4 v[186:189], v184, s[16:17]
	global_load_dwordx4 v[220:223], v184, s[2:3]
	global_load_dwordx4 v[246:249], v184, s[14:15]
	global_load_dwordx4 v[200:203], v184, s[10:11]
	s_add_u32 s16, s16, 0x60000
	s_addc_u32 s17, s17, 0
	s_add_u32 s2, s2, 0x60000
	s_addc_u32 s3, s3, 0
	s_add_u32 s14, s14, 0x60000
	s_addc_u32 s15, s15, 0
	s_add_u32 s10, s10, 0x60000
	s_addc_u32 s11, s11, 0
	ds_read_b128 v[150:153], v208 offset:16384
	ds_read_b128 v[154:157], v208 offset:24576
	s_waitcnt lgkmcnt(10)
	v_mfma_f32_32x32x16_bf16 v[80:95], v[158:161], v[126:129], v[80:95]
	v_mfma_f32_32x32x16_bf16 v[64:79], v[162:165], v[126:129], v[64:79]
	ds_read_b128 v[158:161], v209 offset:16384
	ds_read_b128 v[162:165], v209 offset:24576
	s_waitcnt lgkmcnt(10)
	v_mfma_f32_32x32x16_bf16 v[80:95], v[228:231], v[122:125], v[80:95]
	v_mfma_f32_32x32x16_bf16 v[64:79], v[232:235], v[122:125], v[64:79]
	ds_read_b128 v[228:231], v210 offset:16384
	ds_read_b128 v[232:235], v210 offset:24576
	s_waitcnt lgkmcnt(10)
	v_mfma_f32_32x32x16_bf16 v[80:95], v[236:239], v[118:121], v[80:95]
	v_mfma_f32_32x32x16_bf16 v[64:79], v[240:243], v[118:121], v[64:79]
	ds_read_b128 v[236:239], v211 offset:16384
	ds_read_b128 v[240:243], v211 offset:24576
	s_waitcnt lgkmcnt(6)
	v_mfma_f32_32x32x16_bf16 v[80:95], v[150:153], v[114:117], v[80:95]
	v_mfma_f32_32x32x16_bf16 v[64:79], v[154:157], v[114:117], v[64:79]
	ds_read_b64_tr_b16 v[150:151], v196 offset:0
	ds_read_b64_tr_b16 v[152:153], v196 offset:2048
	ds_read_b64_tr_b16 v[154:155], v196 offset:4096
	ds_read_b64_tr_b16 v[156:157], v196 offset:6144
	s_waitcnt lgkmcnt(8)
	v_mfma_f32_32x32x16_bf16 v[80:95], v[158:161], v[110:113], v[80:95]
	v_mfma_f32_32x32x16_bf16 v[64:79], v[162:165], v[110:113], v[64:79]
	ds_read_b64_tr_b16 v[158:159], v196 offset:8192
	ds_read_b64_tr_b16 v[160:161], v196 offset:10240
	ds_read_b64_tr_b16 v[162:163], v196 offset:12288
	ds_read_b64_tr_b16 v[164:165], v196 offset:14336
	s_waitcnt lgkmcnt(10)
	v_mfma_f32_32x32x16_bf16 v[80:95], v[228:231], v[106:109], v[80:95]
	v_mfma_f32_32x32x16_bf16 v[64:79], v[232:235], v[106:109], v[64:79]
	ds_read_b64_tr_b16 v[228:229], v196 offset:512
	ds_read_b64_tr_b16 v[230:231], v196 offset:2560
	ds_read_b64_tr_b16 v[232:233], v196 offset:4608
	ds_read_b64_tr_b16 v[234:235], v196 offset:6656
	s_waitcnt lgkmcnt(12)
	v_mfma_f32_32x32x16_bf16 v[80:95], v[236:239], v[102:105], v[80:95]
	v_mfma_f32_32x32x16_bf16 v[64:79], v[240:243], v[102:105], v[64:79]
	ds_read_b64_tr_b16 v[236:237], v196 offset:8704
	ds_read_b64_tr_b16 v[238:239], v196 offset:10752
	s_waitcnt lgkmcnt(12)
	v_mfma_f32_32x32x16_bf16 v[0:15], v[166:169], v[150:153], v[0:15]
	ds_read_b64_tr_b16 v[240:241], v196 offset:12800
	ds_read_b64_tr_b16 v[242:243], v196 offset:14848
	s_waitcnt lgkmcnt(12)
	v_mfma_f32_32x32x16_bf16 v[0:15], v[170:173], v[154:157], v[0:15]
	ds_read_b64_tr_b16 v[150:151], v196 offset:1024
	ds_read_b64_tr_b16 v[152:153], v196 offset:3072
	s_waitcnt lgkmcnt(12)
	v_mfma_f32_32x32x16_bf16 v[0:15], v[176:179], v[158:161], v[0:15]
	ds_read_b64_tr_b16 v[154:155], v196 offset:5120
	ds_read_b64_tr_b16 v[156:157], v196 offset:7168
	s_waitcnt lgkmcnt(12)
	v_mfma_f32_32x32x16_bf16 v[0:15], v[180:183], v[162:165], v[0:15]
	ds_read_b64_tr_b16 v[158:159], v196 offset:9216
	ds_read_b64_tr_b16 v[160:161], v196 offset:11264
	s_waitcnt lgkmcnt(12)
	v_mfma_f32_32x32x16_bf16 v[48:63], v[166:169], v[228:231], v[48:63]
	ds_read_b64_tr_b16 v[162:163], v196 offset:13312
	ds_read_b64_tr_b16 v[164:165], v196 offset:15360
	s_waitcnt lgkmcnt(12)
	v_mfma_f32_32x32x16_bf16 v[48:63], v[170:173], v[232:235], v[48:63]
	ds_read_b64_tr_b16 v[228:229], v196 offset:1536
	ds_read_b64_tr_b16 v[230:231], v196 offset:3584
	s_waitcnt lgkmcnt(12)
	v_mfma_f32_32x32x16_bf16 v[48:63], v[176:179], v[236:239], v[48:63]
	ds_read_b64_tr_b16 v[232:233], v196 offset:5632
	ds_read_b64_tr_b16 v[234:235], v196 offset:7680
	s_waitcnt lgkmcnt(12)
	v_mfma_f32_32x32x16_bf16 v[48:63], v[180:183], v[240:243], v[48:63]
	ds_read_b64_tr_b16 v[236:237], v196 offset:9728
	ds_read_b64_tr_b16 v[238:239], v196 offset:11776
	s_waitcnt lgkmcnt(12)
	v_mfma_f32_32x32x16_bf16 v[32:47], v[166:169], v[150:153], v[32:47]
	ds_read_b64_tr_b16 v[240:241], v196 offset:13824
	ds_read_b64_tr_b16 v[242:243], v196 offset:15872
	s_waitcnt lgkmcnt(12)
	v_mfma_f32_32x32x16_bf16 v[32:47], v[170:173], v[154:157], v[32:47]
	s_waitcnt lgkmcnt(10)
	v_mfma_f32_32x32x16_bf16 v[32:47], v[176:179], v[158:161], v[32:47]
	s_waitcnt lgkmcnt(8)
	v_mfma_f32_32x32x16_bf16 v[32:47], v[180:183], v[162:165], v[32:47]
	s_waitcnt lgkmcnt(6)
	v_mfma_f32_32x32x16_bf16 v[16:31], v[166:169], v[228:231], v[16:31]
	s_waitcnt lgkmcnt(4)
	v_mfma_f32_32x32x16_bf16 v[16:31], v[170:173], v[232:235], v[16:31]
	s_waitcnt lgkmcnt(2)
	v_mfma_f32_32x32x16_bf16 v[16:31], v[176:179], v[236:239], v[16:31]
	s_waitcnt lgkmcnt(0)
	v_mfma_f32_32x32x16_bf16 v[16:31], v[180:183], v[240:243], v[16:31]
	s_setprio 0
	s_barrier
; __device__ __forceinline__ void partialSM(f32x16& p0, f32x16& p1, float& m_reg, float& mn, float& alpha) {
;   constexpr float C = SCALE * 1.4426950408889634f;
;   float pmax = p0[0];
; #pragma unroll
;   for (int r = 1; r < 16; ++r) pmax = fmaxf(pmax, p0[r]);
; #pragma unroll
;   for (int r = 0; r < 16; ++r) pmax = fmaxf(pmax, p1[r]);
;   { auto rr = __builtin_amdgcn_permlane32_swap(__float_as_uint(pmax), __float_as_uint(pmax), false, false);
;     pmax = fmaxf(__uint_as_float(rr[0]), __uint_as_float(rr[1])); }
;   if (__builtin_expect(__all(pmax - m_reg <= THR / SCALE), 1)) { mn = m_reg; alpha = 1.f; }
;   else { mn = fmaxf(m_reg, pmax); alpha = __builtin_amdgcn_exp2f((m_reg - mn) * C); m_reg = mn; }
;   float mnC = -mn * C;
; #pragma unroll
;   for (int r = 0; r < 16; ++r) p0[r] = fmaf(p0[r], C, mnC);
; #pragma unroll
;   for (int r = 0; r < 16; ++r) p1[r] = fmaf(p1[r], C, mnC);
; #pragma unroll
;   for (int r = 0; r < 16; ++r) p0[r] = __builtin_amdgcn_exp2f(p0[r]);
; }
	v_max3_f32 v190, v80, v81, v82
	v_max3_f32 v191, v64, v65, v66
	v_max3_f32 v190, v190, v83, v84
	v_max3_f32 v191, v191, v67, v68
	v_max3_f32 v190, v190, v85, v86
	v_max3_f32 v191, v191, v69, v70
	v_max3_f32 v190, v190, v87, v88
	v_max3_f32 v191, v191, v71, v72
	v_max3_f32 v190, v190, v89, v90
	v_max3_f32 v191, v191, v73, v74
	v_max3_f32 v190, v190, v91, v92
	v_max3_f32 v191, v191, v75, v76
	v_max3_f32 v190, v190, v93, v94
	v_max3_f32 v191, v191, v77, v78
	v_max3_f32 v190, v190, v95, v79
	v_max_f32_e32 v190, v190, v191
	v_mov_b32_e32 v191, v190
	s_nop 1
	v_permlane32_swap_b32_e32 v190, v191
	s_nop 0
	v_max_f32_e32 v212, v190, v191
	v_sub_f32_e32 v190, v212, v174
	v_cmp_ge_f32_e32 vcc, s86, v190
	s_nop 3
	s_cmp_eq_u64 vcc, exec
	s_cbranch_scc1 .Lda_common_1
	v_max_f32_e32 v191, v174, v212
	v_sub_f32_e32 v215, v174, v191
	v_mul_f32_e32 v215, s92, v215
	v_exp_f32_e32 v213, v215
	v_mov_b32_e32 v174, v191
	v_mul_f32_e32 v214, 0xbe0293ee, v174
	v_mul_f32_e32 v175, v175, v213
	s_and_saveexec_b64 s[12:13], s[40:41]
	ds_write_b32 v199, v213 offset:128
	s_or_b64 exec, exec, s[12:13]
	s_waitcnt lgkmcnt(0)
	v_add_u32_e32 v215, v99, v96
	ds_read_b128 v[228:231], v215 offset:128
	ds_read_b128 v[232:235], v215 offset:160
	ds_read_b128 v[236:239], v215 offset:192
	ds_read_b128 v[240:243], v215 offset:224
	s_waitcnt lgkmcnt(0)
	v_pk_mul_f32 v[0:1], v[0:1], v[228:229]
	v_pk_mul_f32 v[2:3], v[2:3], v[230:231]
	v_pk_mul_f32 v[4:5], v[4:5], v[232:233]
	v_pk_mul_f32 v[6:7], v[6:7], v[234:235]
	v_pk_mul_f32 v[8:9], v[8:9], v[236:237]
	v_pk_mul_f32 v[10:11], v[10:11], v[238:239]
	v_pk_mul_f32 v[12:13], v[12:13], v[240:241]
	v_pk_mul_f32 v[14:15], v[14:15], v[242:243]
	v_pk_mul_f32 v[48:49], v[48:49], v[228:229]
	v_pk_mul_f32 v[50:51], v[50:51], v[230:231]
	v_pk_mul_f32 v[52:53], v[52:53], v[232:233]
	v_pk_mul_f32 v[54:55], v[54:55], v[234:235]
	v_pk_mul_f32 v[56:57], v[56:57], v[236:237]
	v_pk_mul_f32 v[58:59], v[58:59], v[238:239]
	v_pk_mul_f32 v[60:61], v[60:61], v[240:241]
	v_pk_mul_f32 v[62:63], v[62:63], v[242:243]
	v_pk_mul_f32 v[32:33], v[32:33], v[228:229]
	v_pk_mul_f32 v[34:35], v[34:35], v[230:231]
	v_pk_mul_f32 v[36:37], v[36:37], v[232:233]
	v_pk_mul_f32 v[38:39], v[38:39], v[234:235]
	v_pk_mul_f32 v[40:41], v[40:41], v[236:237]
	v_pk_mul_f32 v[42:43], v[42:43], v[238:239]
	v_pk_mul_f32 v[44:45], v[44:45], v[240:241]
	v_pk_mul_f32 v[46:47], v[46:47], v[242:243]
	v_pk_mul_f32 v[16:17], v[16:17], v[228:229]
	v_pk_mul_f32 v[18:19], v[18:19], v[230:231]
	v_pk_mul_f32 v[20:21], v[20:21], v[232:233]
	v_pk_mul_f32 v[22:23], v[22:23], v[234:235]
	v_pk_mul_f32 v[24:25], v[24:25], v[236:237]
	v_pk_mul_f32 v[26:27], v[26:27], v[238:239]
	v_pk_mul_f32 v[28:29], v[28:29], v[240:241]
	v_pk_mul_f32 v[30:31], v[30:31], v[242:243]

; __device__ __forceinline__ void partialSM(f32x16& p0, f32x16& p1, float& m_reg, float& mn, float& alpha) {
;     ...
;   for (int r = 0; r < 16; ++r) p0[r] = __builtin_amdgcn_exp2f(p0[r]);
; }
; __device__ __forceinline__ void finishSM(f32x16& p0, f32x16& p1, float alpha, float& l_reg, bf16x8& pa0, bf16x8& pa1, bf16x8& pa2, bf16x8& pa3) {
; #pragma unroll
;   for (int r = 0; r < 16; ++r) p1[r] = __builtin_amdgcn_exp2f(p1[r]);
;   float ps = 0;
; #pragma unroll
;   for (int r = 0; r < 16; ++r) ps += p0[r];
; #pragma unroll
;   for (int r = 0; r < 16; ++r) ps += p1[r];
;   { auto rr = __builtin_amdgcn_permlane32_swap(__float_as_uint(ps), __float_as_uint(ps), false, false);
;     ps = __uint_as_float(rr[0]) + __uint_as_float(rr[1]); }
;   l_reg = l_reg * alpha + ps;
;     ...
;   PK4(p0, 0, pa0); PK4(p0, 8, pa1); PK4(p1, 0, pa2); PK4(p1, 8, pa3);
;     ...
; }
; __device__ __forceinline__ void qkt(f32x16& p0, f32x16& p1, const bf16_t* Ks, const bf16x8* qr, int r32, int hi) {
;   p0 = f32x16{}; p1 = f32x16{};
; #pragma unroll
;   for (int d0 = 0; d0 < 8; ++d0) { int cb = (d0 * 16 + hi * 8) * 2;
;     bf16x8 b0 = *reinterpret_cast<const bf16x8*>((const char*)Ks + KSWZ(r32, cb));
;     bf16x8 b1 = *reinterpret_cast<const bf16x8*>((const char*)Ks + KSWZ(32 + r32, cb));
;     p0 = __builtin_amdgcn_mfma_f32_32x32x16_bf16(b0, qr[d0], p0, 0, 0, 0);
;     p1 = __builtin_amdgcn_mfma_f32_32x32x16_bf16(b1, qr[d0], p1, 0, 0, 0); }
.Lda_noresc_1:
	v_exp_f32_e32 v80, v80
	v_exp_f32_e32 v81, v81
	v_exp_f32_e32 v82, v82
	v_exp_f32_e32 v83, v83
	v_exp_f32_e32 v84, v84
	v_exp_f32_e32 v85, v85
	v_exp_f32_e32 v86, v86
	v_exp_f32_e32 v87, v87
	v_exp_f32_e32 v88, v88
	v_exp_f32_e32 v89, v89
	v_exp_f32_e32 v90, v90
	v_exp_f32_e32 v91, v91
	v_exp_f32_e32 v92, v92
	v_exp_f32_e32 v93, v93
	v_exp_f32_e32 v94, v94
	v_exp_f32_e32 v95, v95
	v_exp_f32_e32 v64, v64
	v_exp_f32_e32 v65, v65
	v_exp_f32_e32 v66, v66
	v_exp_f32_e32 v67, v67
	v_exp_f32_e32 v68, v68
	v_exp_f32_e32 v69, v69
	v_exp_f32_e32 v70, v70
	v_exp_f32_e32 v71, v71
	v_exp_f32_e32 v72, v72
	v_exp_f32_e32 v73, v73
	v_exp_f32_e32 v74, v74
	v_exp_f32_e32 v75, v75
	v_exp_f32_e32 v76, v76
	v_exp_f32_e32 v77, v77
	v_exp_f32_e32 v78, v78
	v_exp_f32_e32 v79, v79
	v_add_f32_e32 v190, v80, v81
	v_add_f32_e32 v191, v82, v83
	v_add_f32_e32 v190, v190, v84
	v_add_f32_e32 v191, v191, v85
	v_add_f32_e32 v190, v190, v86
	v_add_f32_e32 v191, v191, v87
	v_add_f32_e32 v190, v190, v88
	v_add_f32_e32 v191, v191, v89
	v_add_f32_e32 v190, v190, v90
	v_add_f32_e32 v191, v191, v91
	v_add_f32_e32 v190, v190, v92
	v_add_f32_e32 v191, v191, v93
	v_add_f32_e32 v190, v190, v94
	v_add_f32_e32 v191, v191, v95
	v_add_f32_e32 v190, v190, v64
	v_add_f32_e32 v191, v191, v65
	v_add_f32_e32 v190, v190, v66
	v_add_f32_e32 v191, v191, v67
	v_add_f32_e32 v190, v190, v68
	v_add_f32_e32 v191, v191, v69
	v_add_f32_e32 v190, v190, v70
	v_add_f32_e32 v191, v191, v71
	v_add_f32_e32 v190, v190, v72
	v_add_f32_e32 v191, v191, v73
	v_add_f32_e32 v190, v190, v74
	v_add_f32_e32 v191, v191, v75
	v_add_f32_e32 v190, v190, v76
	v_add_f32_e32 v191, v191, v77
	v_add_f32_e32 v190, v190, v78
	v_add_f32_e32 v191, v191, v79
	v_add_f32_e32 v190, v190, v191
	v_mov_b32_e32 v191, v190
	v_cvt_pk_bf16_f32 v166, v80, v81
	v_cvt_pk_bf16_f32 v167, v82, v83
	v_cvt_pk_bf16_f32 v168, v84, v85
	v_cvt_pk_bf16_f32 v169, v86, v87
	v_cvt_pk_bf16_f32 v170, v88, v89
	v_cvt_pk_bf16_f32 v171, v90, v91
	v_cvt_pk_bf16_f32 v172, v92, v93
	v_cvt_pk_bf16_f32 v173, v94, v95
	v_cvt_pk_bf16_f32 v176, v64, v65
	v_cvt_pk_bf16_f32 v177, v66, v67
	v_cvt_pk_bf16_f32 v178, v68, v69
	v_cvt_pk_bf16_f32 v179, v70, v71
	v_cvt_pk_bf16_f32 v180, v72, v73
	v_cvt_pk_bf16_f32 v181, v74, v75
	v_cvt_pk_bf16_f32 v182, v76, v77
	v_cvt_pk_bf16_f32 v183, v78, v79
	s_nop 1
	v_permlane32_swap_b32_e32 v190, v191
	v_permlane32_swap_b32_e32 v166, v168
	v_permlane32_swap_b32_e32 v167, v169
	v_permlane32_swap_b32_e32 v170, v172
	v_permlane32_swap_b32_e32 v171, v173
	v_permlane32_swap_b32_e32 v176, v178
	v_permlane32_swap_b32_e32 v177, v179
	v_permlane32_swap_b32_e32 v180, v182
	v_permlane32_swap_b32_e32 v181, v183
	v_add_f32_e32 v190, v190, v191
	v_add_f32_e32 v175, v175, v190
	s_add_u32 s31, s31, 1
	s_cmp_lt_u32 s31, 132
	s_cbranch_scc0 .Lda_skipk_1
	ds_read_b128 v[150:153], v204 offset:32768
	ds_read_b128 v[154:157], v204 offset:40960
	ds_read_b128 v[158:161], v205 offset:32768
	ds_read_b128 v[162:165], v205 offset:40960
	ds_read_b128 v[228:231], v206 offset:32768
	ds_read_b128 v[232:235], v206 offset:40960
	ds_read_b128 v[236:239], v207 offset:32768
	ds_read_b128 v[240:243], v207 offset:40960
.Lda_skipk_1:
	s_barrier
	s_setprio 3
	s_waitcnt vmcnt(4)
	ds_write_b128 v197, v[134:137] offset:0
	ds_write_b128 v197, v[138:141] offset:8192
	ds_write_b128 v185, v[142:145] offset:0
	ds_write_b128 v185, v[146:149] offset:8192
	s_waitcnt lgkmcnt(10)
	v_mfma_f32_32x32x16_bf16 v[80:95], v[150:153], v[130:133], 0
	v_mfma_f32_32x32x16_bf16 v[64:79], v[154:157], v[130:133], 0
	global_load_dwordx4 v[134:137], v184, s[16:17]
	global_load_dwordx4 v[138:141], v184, s[2:3]
	global_load_dwordx4 v[142:145], v184, s[14:15]
	global_load_dwordx4 v[146:149], v184, s[10:11]
	s_add_u32 s16, s16, 0x60000
	s_addc_u32 s17, s17, 0
	s_add_u32 s2, s2, 0x60000
	s_addc_u32 s3, s3, 0
	s_add_u32 s14, s14, 0x60000
	s_addc_u32 s15, s15, 0
	s_add_u32 s10, s10, 0x60000
	s_addc_u32 s11, s11, 0
	ds_read_b128 v[150:153], v208 offset:32768
	ds_read_b128 v[154:157], v208 offset:40960
	s_waitcnt lgkmcnt(10)
	v_mfma_f32_32x32x16_bf16 v[80:95], v[158:161], v[126:129], v[80:95]
	v_mfma_f32_32x32x16_bf16 v[64:79], v[162:165], v[126:129], v[64:79]
	ds_read_b128 v[158:161], v209 offset:32768
	ds_read_b128 v[162:165], v209 offset:40960
	s_waitcnt lgkmcnt(10)
	v_mfma_f32_32x32x16_bf16 v[80:95], v[228:231], v[122:125], v[80:95]
	v_mfma_f32_32x32x16_bf16 v[64:79], v[232:235], v[122:125], v[64:79]
	ds_read_b128 v[228:231], v210 offset:32768
	ds_read_b128 v[232:235], v210 offset:40960
	s_waitcnt lgkmcnt(10)
	v_mfma_f32_32x32x16_bf16 v[80:95], v[236:239], v[118:121], v[80:95]
	v_mfma_f32_32x32x16_bf16 v[64:79], v[240:243], v[118:121], v[64:79]
	ds_read_b128 v[236:239], v211 offset:32768
	ds_read_b128 v[240:243], v211 offset:40960
	s_waitcnt lgkmcnt(6)
	v_mfma_f32_32x32x16_bf16 v[80:95], v[150:153], v[114:117], v[80:95]
	v_mfma_f32_32x32x16_bf16 v[64:79], v[154:157], v[114:117], v[64:79]
	ds_read_b64_tr_b16 v[150:151], v196 offset:16384
	ds_read_b64_tr_b16 v[152:153], v196 offset:18432
	ds_read_b64_tr_b16 v[154:155], v196 offset:20480
	ds_read_b64_tr_b16 v[156:157], v196 offset:22528
	s_waitcnt lgkmcnt(8)
	v_mfma_f32_32x32x16_bf16 v[80:95], v[158:161], v[110:113], v[80:95]
	v_mfma_f32_32x32x16_bf16 v[64:79], v[162:165], v[110:113], v[64:79]
	ds_read_b64_tr_b16 v[158:159], v196 offset:24576
	ds_read_b64_tr_b16 v[160:161], v196 offset:26624
	ds_read_b64_tr_b16 v[162:163], v196 offset:28672
	ds_read_b64_tr_b16 v[164:165], v196 offset:30720
	s_waitcnt lgkmcnt(10)
; #define SBAR() __builtin_amdgcn_sched_barrier(0)
; __device__ __forceinline__ void partialSM(f32x16& p0, f32x16& p1, float& m_reg, float& mn, float& alpha) {
;   constexpr float C = SCALE * 1.4426950408889634f;
;   float pmax = p0[0];
; #pragma unroll
;   for (int r = 1; r < 16; ++r) pmax = fmaxf(pmax, p0[r]);
; #pragma unroll
;   for (int r = 0; r < 16; ++r) pmax = fmaxf(pmax, p1[r]);
;   { auto rr = __builtin_amdgcn_permlane32_swap(__float_as_uint(pmax), __float_as_uint(pmax), false, false);
;     pmax = fmaxf(__uint_as_float(rr[0]), __uint_as_float(rr[1])); }
;   if (__builtin_expect(__all(pmax - m_reg <= THR / SCALE), 1)) { mn = m_reg; alpha = 1.f; }
;   else { mn = fmaxf(m_reg, pmax); alpha = __builtin_amdgcn_exp2f((m_reg - mn) * C); m_reg = mn; }
;   float mnC = -mn * C;
; #pragma unroll
;   for (int r = 0; r < 16; ++r) p0[r] = fmaf(p0[r], C, mnC);
; #pragma unroll
;   for (int r = 0; r < 16; ++r) p1[r] = fmaf(p1[r], C, mnC);
; #pragma unroll
;   for (int r = 0; r < 16; ++r) p0[r] = __builtin_amdgcn_exp2f(p0[r]);
; }
; template <int D0> __device__ __forceinline__ void pv_one(f32x16& od, int vb, bf16x8 pa0, bf16x8 pa1, bf16x8 pa2, bf16x8 pa3) {
;   const s16x4 l0 = tr_read<v_rd_off(D0, 0, 0)>(vb), h0 = tr_read<v_rd_off(D0, 0, 1)>(vb), l1 = tr_read<v_rd_off(D0, 1, 0)>(vb), h1 = tr_read<v_rd_off(D0, 1, 1)>(vb);
;   const s16x4 l2 = tr_read<v_rd_off(D0, 2, 0)>(vb), h2 = tr_read<v_rd_off(D0, 2, 1)>(vb), l3 = tr_read<v_rd_off(D0, 3, 0)>(vb), h3 = tr_read<v_rd_off(D0, 3, 1)>(vb);
;   asm volatile("s_waitcnt lgkmcnt(0)" ::: "memory"); SBAR();
;     ...
;   od = __builtin_amdgcn_mfma_f32_32x32x16_bf16(pa0, PK(l0, h0), od, 0, 0, 0);
;   od = __builtin_amdgcn_mfma_f32_32x32x16_bf16(pa1, PK(l1, h1), od, 0, 0, 0);
;   od = __builtin_amdgcn_mfma_f32_32x32x16_bf16(pa2, PK(l2, h2), od, 0, 0, 0);
;   od = __builtin_amdgcn_mfma_f32_32x32x16_bf16(pa3, PK(l3, h3), od, 0, 0, 0);
;     ...
; }
	v_mfma_f32_32x32x16_bf16 v[80:95], v[228:231], v[106:109], v[80:95]
	v_mfma_f32_32x32x16_bf16 v[64:79], v[232:235], v[106:109], v[64:79]
	ds_read_b64_tr_b16 v[228:229], v196 offset:16896
	ds_read_b64_tr_b16 v[230:231], v196 offset:18944
	ds_read_b64_tr_b16 v[232:233], v196 offset:20992
	ds_read_b64_tr_b16 v[234:235], v196 offset:23040
	s_waitcnt lgkmcnt(12)
	v_mfma_f32_32x32x16_bf16 v[80:95], v[236:239], v[102:105], v[80:95]
	v_mfma_f32_32x32x16_bf16 v[64:79], v[240:243], v[102:105], v[64:79]
	ds_read_b64_tr_b16 v[236:237], v196 offset:25088
	ds_read_b64_tr_b16 v[238:239], v196 offset:27136
	s_waitcnt lgkmcnt(12)
	v_mfma_f32_32x32x16_bf16 v[0:15], v[166:169], v[150:153], v[0:15]
	ds_read_b64_tr_b16 v[240:241], v196 offset:29184
	ds_read_b64_tr_b16 v[242:243], v196 offset:31232
	s_waitcnt lgkmcnt(12)
	v_mfma_f32_32x32x16_bf16 v[0:15], v[170:173], v[154:157], v[0:15]
	ds_read_b64_tr_b16 v[150:151], v196 offset:17408
	ds_read_b64_tr_b16 v[152:153], v196 offset:19456
	s_waitcnt lgkmcnt(12)
	v_mfma_f32_32x32x16_bf16 v[0:15], v[176:179], v[158:161], v[0:15]
	ds_read_b64_tr_b16 v[154:155], v196 offset:21504
	ds_read_b64_tr_b16 v[156:157], v196 offset:23552
	s_waitcnt lgkmcnt(12)
	v_mfma_f32_32x32x16_bf16 v[0:15], v[180:183], v[162:165], v[0:15]
	ds_read_b64_tr_b16 v[158:159], v196 offset:25600
	ds_read_b64_tr_b16 v[160:161], v196 offset:27648
	s_waitcnt lgkmcnt(12)
	v_mfma_f32_32x32x16_bf16 v[48:63], v[166:169], v[228:231], v[48:63]
	ds_read_b64_tr_b16 v[162:163], v196 offset:29696
	ds_read_b64_tr_b16 v[164:165], v196 offset:31744
	s_waitcnt lgkmcnt(12)
	v_mfma_f32_32x32x16_bf16 v[48:63], v[170:173], v[232:235], v[48:63]
	ds_read_b64_tr_b16 v[228:229], v196 offset:17920
	ds_read_b64_tr_b16 v[230:231], v196 offset:19968
	s_waitcnt lgkmcnt(12)
	v_mfma_f32_32x32x16_bf16 v[48:63], v[176:179], v[236:239], v[48:63]
	ds_read_b64_tr_b16 v[232:233], v196 offset:22016
	ds_read_b64_tr_b16 v[234:235], v196 offset:24064
	s_waitcnt lgkmcnt(12)
	v_mfma_f32_32x32x16_bf16 v[48:63], v[180:183], v[240:243], v[48:63]
	ds_read_b64_tr_b16 v[236:237], v196 offset:26112
	ds_read_b64_tr_b16 v[238:239], v196 offset:28160
	s_waitcnt lgkmcnt(12)
	v_mfma_f32_32x32x16_bf16 v[32:47], v[166:169], v[150:153], v[32:47]
	ds_read_b64_tr_b16 v[240:241], v196 offset:30208
	ds_read_b64_tr_b16 v[242:243], v196 offset:32256
	s_waitcnt lgkmcnt(12)
	v_mfma_f32_32x32x16_bf16 v[32:47], v[170:173], v[154:157], v[32:47]
	s_waitcnt lgkmcnt(10)
	v_mfma_f32_32x32x16_bf16 v[32:47], v[176:179], v[158:161], v[32:47]
	s_waitcnt lgkmcnt(8)
	v_mfma_f32_32x32x16_bf16 v[32:47], v[180:183], v[162:165], v[32:47]
	s_waitcnt lgkmcnt(6)
	v_mfma_f32_32x32x16_bf16 v[16:31], v[166:169], v[228:231], v[16:31]
	s_waitcnt lgkmcnt(4)
	v_mfma_f32_32x32x16_bf16 v[16:31], v[170:173], v[232:235], v[16:31]
	s_waitcnt lgkmcnt(2)
	v_mfma_f32_32x32x16_bf16 v[16:31], v[176:179], v[236:239], v[16:31]
	s_waitcnt lgkmcnt(0)
	v_mfma_f32_32x32x16_bf16 v[16:31], v[180:183], v[240:243], v[16:31]
	s_setprio 0
	s_barrier
	v_max3_f32 v190, v80, v81, v82
	v_max3_f32 v191, v64, v65, v66
	v_max3_f32 v190, v190, v83, v84
	v_max3_f32 v191, v191, v67, v68
	v_max3_f32 v190, v190, v85, v86
	v_max3_f32 v191, v191, v69, v70
	v_max3_f32 v190, v190, v87, v88
	v_max3_f32 v191, v191, v71, v72
	v_max3_f32 v190, v190, v89, v90
	v_max3_f32 v191, v191, v73, v74
	v_max3_f32 v190, v190, v91, v92
	v_max3_f32 v191, v191, v75, v76
	v_max3_f32 v190, v190, v93, v94
	v_max3_f32 v191, v191, v77, v78
	v_max3_f32 v190, v190, v95, v79
	v_max_f32_e32 v190, v190, v191
	v_mov_b32_e32 v191, v190
	s_nop 1
	v_permlane32_swap_b32_e32 v190, v191
	s_nop 0
	v_max_f32_e32 v212, v190, v191
	v_sub_f32_e32 v190, v212, v174
	v_cmp_ge_f32_e32 vcc, s86, v190
	s_nop 3
	s_cmp_eq_u64 vcc, exec
	s_cbranch_scc1 .Lda_common_2
	v_max_f32_e32 v191, v174, v212
	v_sub_f32_e32 v215, v174, v191
	v_mul_f32_e32 v215, s92, v215
	v_exp_f32_e32 v213, v215
	v_mov_b32_e32 v174, v191
	v_mul_f32_e32 v214, 0xbe0293ee, v174
	v_mul_f32_e32 v175, v175, v213
	s_and_saveexec_b64 s[12:13], s[40:41]
	ds_write_b32 v199, v213 offset:128
	s_or_b64 exec, exec, s[12:13]
	s_waitcnt lgkmcnt(0)
	v_add_u32_e32 v215, v99, v96
	ds_read_b128 v[228:231], v215 offset:128
	ds_read_b128 v[232:235], v215 offset:160
	ds_read_b128 v[236:239], v215 offset:192
	ds_read_b128 v[240:243], v215 offset:224
	s_waitcnt lgkmcnt(0)
	v_pk_mul_f32 v[0:1], v[0:1], v[228:229]
	v_pk_mul_f32 v[2:3], v[2:3], v[230:231]
	v_pk_mul_f32 v[4:5], v[4:5], v[232:233]
	v_pk_mul_f32 v[6:7], v[6:7], v[234:235]
	v_pk_mul_f32 v[8:9], v[8:9], v[236:237]
	v_pk_mul_f32 v[10:11], v[10:11], v[238:239]
	v_pk_mul_f32 v[12:13], v[12:13], v[240:241]
	v_pk_mul_f32 v[14:15], v[14:15], v[242:243]
	v_pk_mul_f32 v[48:49], v[48:49], v[228:229]
	v_pk_mul_f32 v[50:51], v[50:51], v[230:231]
	v_pk_mul_f32 v[52:53], v[52:53], v[232:233]
	v_pk_mul_f32 v[54:55], v[54:55], v[234:235]
	v_pk_mul_f32 v[56:57], v[56:57], v[236:237]
	v_pk_mul_f32 v[58:59], v[58:59], v[238:239]
	v_pk_mul_f32 v[60:61], v[60:61], v[240:241]
	v_pk_mul_f32 v[62:63], v[62:63], v[242:243]
	v_pk_mul_f32 v[32:33], v[32:33], v[228:229]
	v_pk_mul_f32 v[34:35], v[34:35], v[230:231]
	v_pk_mul_f32 v[36:37], v[36:37], v[232:233]
	v_pk_mul_f32 v[38:39], v[38:39], v[234:235]
	v_pk_mul_f32 v[40:41], v[40:41], v[236:237]
	v_pk_mul_f32 v[42:43], v[42:43], v[238:239]
	v_pk_mul_f32 v[44:45], v[44:45], v[240:241]
	v_pk_mul_f32 v[46:47], v[46:47], v[242:243]
	v_pk_mul_f32 v[16:17], v[16:17], v[228:229]
	v_pk_mul_f32 v[18:19], v[18:19], v[230:231]
	v_pk_mul_f32 v[20:21], v[20:21], v[232:233]
	v_pk_mul_f32 v[22:23], v[22:23], v[234:235]
	v_pk_mul_f32 v[24:25], v[24:25], v[236:237]
	v_pk_mul_f32 v[26:27], v[26:27], v[238:239]
	v_pk_mul_f32 v[28:29], v[28:29], v[240:241]
	v_pk_mul_f32 v[30:31], v[30:31], v[242:243]

; __device__ __forceinline__ void partialSM(f32x16& p0, f32x16& p1, float& m_reg, float& mn, float& alpha) {
;     ...
;   for (int r = 0; r < 16; ++r) p0[r] = __builtin_amdgcn_exp2f(p0[r]);
; }
; __device__ __forceinline__ void finishSM(f32x16& p0, f32x16& p1, float alpha, float& l_reg, bf16x8& pa0, bf16x8& pa1, bf16x8& pa2, bf16x8& pa3) {
; #pragma unroll
;   for (int r = 0; r < 16; ++r) p1[r] = __builtin_amdgcn_exp2f(p1[r]);
;   float ps = 0;
; #pragma unroll
;   for (int r = 0; r < 16; ++r) ps += p0[r];
; #pragma unroll
;   for (int r = 0; r < 16; ++r) ps += p1[r];
;   { auto rr = __builtin_amdgcn_permlane32_swap(__float_as_uint(ps), __float_as_uint(ps), false, false);
;     ps = __uint_as_float(rr[0]) + __uint_as_float(rr[1]); }
;   l_reg = l_reg * alpha + ps;
;     ...
;   PK4(p0, 0, pa0); PK4(p0, 8, pa1); PK4(p1, 0, pa2); PK4(p1, 8, pa3);
;     ...
; }
; __device__ __forceinline__ void qkt(f32x16& p0, f32x16& p1, const bf16_t* Ks, const bf16x8* qr, int r32, int hi) {
;   p0 = f32x16{}; p1 = f32x16{};
; #pragma unroll
;   for (int d0 = 0; d0 < 8; ++d0) { int cb = (d0 * 16 + hi * 8) * 2;
;     bf16x8 b0 = *reinterpret_cast<const bf16x8*>((const char*)Ks + KSWZ(r32, cb));
;     bf16x8 b1 = *reinterpret_cast<const bf16x8*>((const char*)Ks + KSWZ(32 + r32, cb));
;     p0 = __builtin_amdgcn_mfma_f32_32x32x16_bf16(b0, qr[d0], p0, 0, 0, 0);
;     p1 = __builtin_amdgcn_mfma_f32_32x32x16_bf16(b1, qr[d0], p1, 0, 0, 0); }
.Lda_noresc_2:
	v_exp_f32_e32 v80, v80
	v_exp_f32_e32 v81, v81
	v_exp_f32_e32 v82, v82
	v_exp_f32_e32 v83, v83
	v_exp_f32_e32 v84, v84
	v_exp_f32_e32 v85, v85
	v_exp_f32_e32 v86, v86
	v_exp_f32_e32 v87, v87
	v_exp_f32_e32 v88, v88
	v_exp_f32_e32 v89, v89
	v_exp_f32_e32 v90, v90
	v_exp_f32_e32 v91, v91
	v_exp_f32_e32 v92, v92
	v_exp_f32_e32 v93, v93
	v_exp_f32_e32 v94, v94
	v_exp_f32_e32 v95, v95
	v_exp_f32_e32 v64, v64
	v_exp_f32_e32 v65, v65
	v_exp_f32_e32 v66, v66
	v_exp_f32_e32 v67, v67
	v_exp_f32_e32 v68, v68
	v_exp_f32_e32 v69, v69
	v_exp_f32_e32 v70, v70
	v_exp_f32_e32 v71, v71
	v_exp_f32_e32 v72, v72
	v_exp_f32_e32 v73, v73
	v_exp_f32_e32 v74, v74
	v_exp_f32_e32 v75, v75
	v_exp_f32_e32 v76, v76
	v_exp_f32_e32 v77, v77
	v_exp_f32_e32 v78, v78
	v_exp_f32_e32 v79, v79
	v_add_f32_e32 v190, v80, v81
	v_add_f32_e32 v191, v82, v83
	v_add_f32_e32 v190, v190, v84
	v_add_f32_e32 v191, v191, v85
	v_add_f32_e32 v190, v190, v86
	v_add_f32_e32 v191, v191, v87
	v_add_f32_e32 v190, v190, v88
	v_add_f32_e32 v191, v191, v89
	v_add_f32_e32 v190, v190, v90
	v_add_f32_e32 v191, v191, v91
	v_add_f32_e32 v190, v190, v92
	v_add_f32_e32 v191, v191, v93
	v_add_f32_e32 v190, v190, v94
	v_add_f32_e32 v191, v191, v95
	v_add_f32_e32 v190, v190, v64
	v_add_f32_e32 v191, v191, v65
	v_add_f32_e32 v190, v190, v66
	v_add_f32_e32 v191, v191, v67
	v_add_f32_e32 v190, v190, v68
	v_add_f32_e32 v191, v191, v69
	v_add_f32_e32 v190, v190, v70
	v_add_f32_e32 v191, v191, v71
	v_add_f32_e32 v190, v190, v72
	v_add_f32_e32 v191, v191, v73
	v_add_f32_e32 v190, v190, v74
	v_add_f32_e32 v191, v191, v75
	v_add_f32_e32 v190, v190, v76
	v_add_f32_e32 v191, v191, v77
	v_add_f32_e32 v190, v190, v78
	v_add_f32_e32 v191, v191, v79
	v_add_f32_e32 v190, v190, v191
	v_mov_b32_e32 v191, v190
	v_cvt_pk_bf16_f32 v166, v80, v81
	v_cvt_pk_bf16_f32 v167, v82, v83
	v_cvt_pk_bf16_f32 v168, v84, v85
	v_cvt_pk_bf16_f32 v169, v86, v87
	v_cvt_pk_bf16_f32 v170, v88, v89
	v_cvt_pk_bf16_f32 v171, v90, v91
	v_cvt_pk_bf16_f32 v172, v92, v93
	v_cvt_pk_bf16_f32 v173, v94, v95
	v_cvt_pk_bf16_f32 v176, v64, v65
	v_cvt_pk_bf16_f32 v177, v66, v67
	v_cvt_pk_bf16_f32 v178, v68, v69
	v_cvt_pk_bf16_f32 v179, v70, v71
	v_cvt_pk_bf16_f32 v180, v72, v73
	v_cvt_pk_bf16_f32 v181, v74, v75
	v_cvt_pk_bf16_f32 v182, v76, v77
	v_cvt_pk_bf16_f32 v183, v78, v79
	s_nop 1
	v_permlane32_swap_b32_e32 v190, v191
	v_permlane32_swap_b32_e32 v166, v168
	v_permlane32_swap_b32_e32 v167, v169
	v_permlane32_swap_b32_e32 v170, v172
	v_permlane32_swap_b32_e32 v171, v173
	v_permlane32_swap_b32_e32 v176, v178
	v_permlane32_swap_b32_e32 v177, v179
	v_permlane32_swap_b32_e32 v180, v182
	v_permlane32_swap_b32_e32 v181, v183
	v_add_f32_e32 v190, v190, v191
	v_add_f32_e32 v175, v175, v190
	s_add_u32 s31, s31, 1
	s_cmp_lt_u32 s31, 132
	s_cbranch_scc0 .Lda_skipk_2
	ds_read_b128 v[150:153], v204 offset:49152
	ds_read_b128 v[154:157], v204 offset:57344
	ds_read_b128 v[158:161], v205 offset:49152
	ds_read_b128 v[162:165], v205 offset:57344
	ds_read_b128 v[228:231], v206 offset:49152
	ds_read_b128 v[232:235], v206 offset:57344
	ds_read_b128 v[236:239], v207 offset:49152
	ds_read_b128 v[240:243], v207 offset:57344
.Lda_skipk_2:
	s_barrier
	s_setprio 3
	s_waitcnt vmcnt(4)
	ds_write_b128 v197, v[186:189] offset:16384
	ds_write_b128 v197, v[220:223] offset:24576
	ds_write_b128 v185, v[246:249] offset:16384
	ds_write_b128 v185, v[200:203] offset:24576
	s_waitcnt lgkmcnt(10)
	v_mfma_f32_32x32x16_bf16 v[80:95], v[150:153], v[130:133], 0
	v_mfma_f32_32x32x16_bf16 v[64:79], v[154:157], v[130:133], 0
	global_load_dwordx4 v[186:189], v184, s[16:17]
	global_load_dwordx4 v[220:223], v184, s[2:3]
	global_load_dwordx4 v[246:249], v184, s[14:15]
	global_load_dwordx4 v[200:203], v184, s[10:11]
	s_add_u32 s16, s16, 0x60000
	s_addc_u32 s17, s17, 0
	s_add_u32 s2, s2, 0x60000
	s_addc_u32 s3, s3, 0
	s_add_u32 s14, s14, 0x60000
	s_addc_u32 s15, s15, 0
	s_add_u32 s10, s10, 0x60000
	s_addc_u32 s11, s11, 0
	ds_read_b128 v[150:153], v208 offset:49152
	ds_read_b128 v[154:157], v208 offset:57344
	s_waitcnt lgkmcnt(10)
	v_mfma_f32_32x32x16_bf16 v[80:95], v[158:161], v[126:129], v[80:95]
	v_mfma_f32_32x32x16_bf16 v[64:79], v[162:165], v[126:129], v[64:79]
	ds_read_b128 v[158:161], v209 offset:49152
	ds_read_b128 v[162:165], v209 offset:57344
	s_waitcnt lgkmcnt(10)
	v_mfma_f32_32x32x16_bf16 v[80:95], v[228:231], v[122:125], v[80:95]
	v_mfma_f32_32x32x16_bf16 v[64:79], v[232:235], v[122:125], v[64:79]
	ds_read_b128 v[228:231], v210 offset:49152
	ds_read_b128 v[232:235], v210 offset:57344
	s_waitcnt lgkmcnt(10)
	v_mfma_f32_32x32x16_bf16 v[80:95], v[236:239], v[118:121], v[80:95]
	v_mfma_f32_32x32x16_bf16 v[64:79], v[240:243], v[118:121], v[64:79]
	ds_read_b128 v[236:239], v211 offset:49152
	ds_read_b128 v[240:243], v211 offset:57344
	s_waitcnt lgkmcnt(6)
	v_mfma_f32_32x32x16_bf16 v[80:95], v[150:153], v[114:117], v[80:95]
	v_mfma_f32_32x32x16_bf16 v[64:79], v[154:157], v[114:117], v[64:79]
	ds_read_b64_tr_b16 v[150:151], v196 offset:32768
	ds_read_b64_tr_b16 v[152:153], v196 offset:34816
	ds_read_b64_tr_b16 v[154:155], v196 offset:36864
	ds_read_b64_tr_b16 v[156:157], v196 offset:38912
	s_waitcnt lgkmcnt(8)
	v_mfma_f32_32x32x16_bf16 v[80:95], v[158:161], v[110:113], v[80:95]
	v_mfma_f32_32x32x16_bf16 v[64:79], v[162:165], v[110:113], v[64:79]
	ds_read_b64_tr_b16 v[158:159], v196 offset:40960
	ds_read_b64_tr_b16 v[160:161], v196 offset:43008
	ds_read_b64_tr_b16 v[162:163], v196 offset:45056
	ds_read_b64_tr_b16 v[164:165], v196 offset:47104
	s_waitcnt lgkmcnt(10)
; #define SBAR() __builtin_amdgcn_sched_barrier(0)
; __device__ __forceinline__ void partialSM(f32x16& p0, f32x16& p1, float& m_reg, float& mn, float& alpha) {
;   constexpr float C = SCALE * 1.4426950408889634f;
;   float pmax = p0[0];
; #pragma unroll
;   for (int r = 1; r < 16; ++r) pmax = fmaxf(pmax, p0[r]);
; #pragma unroll
;   for (int r = 0; r < 16; ++r) pmax = fmaxf(pmax, p1[r]);
;   { auto rr = __builtin_amdgcn_permlane32_swap(__float_as_uint(pmax), __float_as_uint(pmax), false, false);
;     pmax = fmaxf(__uint_as_float(rr[0]), __uint_as_float(rr[1])); }
;   if (__builtin_expect(__all(pmax - m_reg <= THR / SCALE), 1)) { mn = m_reg; alpha = 1.f; }
;   else { mn = fmaxf(m_reg, pmax); alpha = __builtin_amdgcn_exp2f((m_reg - mn) * C); m_reg = mn; }
;   float mnC = -mn * C;
; #pragma unroll
;   for (int r = 0; r < 16; ++r) p0[r] = fmaf(p0[r], C, mnC);
; #pragma unroll
;   for (int r = 0; r < 16; ++r) p1[r] = fmaf(p1[r], C, mnC);
; #pragma unroll
;   for (int r = 0; r < 16; ++r) p0[r] = __builtin_amdgcn_exp2f(p0[r]);
; }
; template <int D0> __device__ __forceinline__ void pv_one(f32x16& od, int vb, bf16x8 pa0, bf16x8 pa1, bf16x8 pa2, bf16x8 pa3) {
;   const s16x4 l0 = tr_read<v_rd_off(D0, 0, 0)>(vb), h0 = tr_read<v_rd_off(D0, 0, 1)>(vb), l1 = tr_read<v_rd_off(D0, 1, 0)>(vb), h1 = tr_read<v_rd_off(D0, 1, 1)>(vb);
;   const s16x4 l2 = tr_read<v_rd_off(D0, 2, 0)>(vb), h2 = tr_read<v_rd_off(D0, 2, 1)>(vb), l3 = tr_read<v_rd_off(D0, 3, 0)>(vb), h3 = tr_read<v_rd_off(D0, 3, 1)>(vb);
;   asm volatile("s_waitcnt lgkmcnt(0)" ::: "memory"); SBAR();
;     ...
;   od = __builtin_amdgcn_mfma_f32_32x32x16_bf16(pa0, PK(l0, h0), od, 0, 0, 0);
;   od = __builtin_amdgcn_mfma_f32_32x32x16_bf16(pa1, PK(l1, h1), od, 0, 0, 0);
;   od = __builtin_amdgcn_mfma_f32_32x32x16_bf16(pa2, PK(l2, h2), od, 0, 0, 0);
;   od = __builtin_amdgcn_mfma_f32_32x32x16_bf16(pa3, PK(l3, h3), od, 0, 0, 0);
;     ...
; }
	v_mfma_f32_32x32x16_bf16 v[80:95], v[228:231], v[106:109], v[80:95]
	v_mfma_f32_32x32x16_bf16 v[64:79], v[232:235], v[106:109], v[64:79]
	ds_read_b64_tr_b16 v[228:229], v196 offset:33280
	ds_read_b64_tr_b16 v[230:231], v196 offset:35328
	ds_read_b64_tr_b16 v[232:233], v196 offset:37376
	ds_read_b64_tr_b16 v[234:235], v196 offset:39424
	s_waitcnt lgkmcnt(12)
	v_mfma_f32_32x32x16_bf16 v[80:95], v[236:239], v[102:105], v[80:95]
	v_mfma_f32_32x32x16_bf16 v[64:79], v[240:243], v[102:105], v[64:79]
	ds_read_b64_tr_b16 v[236:237], v196 offset:41472
	ds_read_b64_tr_b16 v[238:239], v196 offset:43520
	s_waitcnt lgkmcnt(12)
	v_mfma_f32_32x32x16_bf16 v[0:15], v[166:169], v[150:153], v[0:15]
	ds_read_b64_tr_b16 v[240:241], v196 offset:45568
	ds_read_b64_tr_b16 v[242:243], v196 offset:47616
	s_waitcnt lgkmcnt(12)
	v_mfma_f32_32x32x16_bf16 v[0:15], v[170:173], v[154:157], v[0:15]
	ds_read_b64_tr_b16 v[150:151], v196 offset:33792
	ds_read_b64_tr_b16 v[152:153], v196 offset:35840
	s_waitcnt lgkmcnt(12)
	v_mfma_f32_32x32x16_bf16 v[0:15], v[176:179], v[158:161], v[0:15]
	ds_read_b64_tr_b16 v[154:155], v196 offset:37888
	ds_read_b64_tr_b16 v[156:157], v196 offset:39936
	s_waitcnt lgkmcnt(12)
	v_mfma_f32_32x32x16_bf16 v[0:15], v[180:183], v[162:165], v[0:15]
	ds_read_b64_tr_b16 v[158:159], v196 offset:41984
	ds_read_b64_tr_b16 v[160:161], v196 offset:44032
	s_waitcnt lgkmcnt(12)
	v_mfma_f32_32x32x16_bf16 v[48:63], v[166:169], v[228:231], v[48:63]
	ds_read_b64_tr_b16 v[162:163], v196 offset:46080
	ds_read_b64_tr_b16 v[164:165], v196 offset:48128
	s_waitcnt lgkmcnt(12)
	v_mfma_f32_32x32x16_bf16 v[48:63], v[170:173], v[232:235], v[48:63]
	ds_read_b64_tr_b16 v[228:229], v196 offset:34304
	ds_read_b64_tr_b16 v[230:231], v196 offset:36352
	s_waitcnt lgkmcnt(12)
	v_mfma_f32_32x32x16_bf16 v[48:63], v[176:179], v[236:239], v[48:63]
	ds_read_b64_tr_b16 v[232:233], v196 offset:38400
	ds_read_b64_tr_b16 v[234:235], v196 offset:40448
	s_waitcnt lgkmcnt(12)
	v_mfma_f32_32x32x16_bf16 v[48:63], v[180:183], v[240:243], v[48:63]
	ds_read_b64_tr_b16 v[236:237], v196 offset:42496
	ds_read_b64_tr_b16 v[238:239], v196 offset:44544
	s_waitcnt lgkmcnt(12)
	v_mfma_f32_32x32x16_bf16 v[32:47], v[166:169], v[150:153], v[32:47]
	ds_read_b64_tr_b16 v[240:241], v196 offset:46592
	ds_read_b64_tr_b16 v[242:243], v196 offset:48640
	s_waitcnt lgkmcnt(12)
	v_mfma_f32_32x32x16_bf16 v[32:47], v[170:173], v[154:157], v[32:47]
	s_waitcnt lgkmcnt(10)
	v_mfma_f32_32x32x16_bf16 v[32:47], v[176:179], v[158:161], v[32:47]
	s_waitcnt lgkmcnt(8)
	v_mfma_f32_32x32x16_bf16 v[32:47], v[180:183], v[162:165], v[32:47]
	s_waitcnt lgkmcnt(6)
	v_mfma_f32_32x32x16_bf16 v[16:31], v[166:169], v[228:231], v[16:31]
	s_waitcnt lgkmcnt(4)
	v_mfma_f32_32x32x16_bf16 v[16:31], v[170:173], v[232:235], v[16:31]
	s_waitcnt lgkmcnt(2)
	v_mfma_f32_32x32x16_bf16 v[16:31], v[176:179], v[236:239], v[16:31]
	s_waitcnt lgkmcnt(0)
	v_mfma_f32_32x32x16_bf16 v[16:31], v[180:183], v[240:243], v[16:31]
	s_setprio 0
	s_barrier
	v_max3_f32 v190, v80, v81, v82
	v_max3_f32 v191, v64, v65, v66
	v_max3_f32 v190, v190, v83, v84
	v_max3_f32 v191, v191, v67, v68
	v_max3_f32 v190, v190, v85, v86
	v_max3_f32 v191, v191, v69, v70
	v_max3_f32 v190, v190, v87, v88
	v_max3_f32 v191, v191, v71, v72
	v_max3_f32 v190, v190, v89, v90
	v_max3_f32 v191, v191, v73, v74
	v_max3_f32 v190, v190, v91, v92
	v_max3_f32 v191, v191, v75, v76
	v_max3_f32 v190, v190, v93, v94
	v_max3_f32 v191, v191, v77, v78
	v_max3_f32 v190, v190, v95, v79
	v_max_f32_e32 v190, v190, v191
	v_mov_b32_e32 v191, v190
	s_nop 1
	v_permlane32_swap_b32_e32 v190, v191
	s_nop 0
	v_max_f32_e32 v212, v190, v191
	v_sub_f32_e32 v190, v212, v174
	v_cmp_ge_f32_e32 vcc, s86, v190
	s_nop 3
	s_cmp_eq_u64 vcc, exec
	s_cbranch_scc1 .Lda_common_3
	v_max_f32_e32 v191, v174, v212
	v_sub_f32_e32 v215, v174, v191
	v_mul_f32_e32 v215, s92, v215
	v_exp_f32_e32 v213, v215
	v_mov_b32_e32 v174, v191
	v_mul_f32_e32 v214, 0xbe0293ee, v174
	v_mul_f32_e32 v175, v175, v213
	s_and_saveexec_b64 s[12:13], s[40:41]
	ds_write_b32 v199, v213 offset:128
	s_or_b64 exec, exec, s[12:13]
	s_waitcnt lgkmcnt(0)
	v_add_u32_e32 v215, v99, v96
	ds_read_b128 v[228:231], v215 offset:128
	ds_read_b128 v[232:235], v215 offset:160
	ds_read_b128 v[236:239], v215 offset:192
	ds_read_b128 v[240:243], v215 offset:224
	s_waitcnt lgkmcnt(0)
	v_pk_mul_f32 v[0:1], v[0:1], v[228:229]
	v_pk_mul_f32 v[2:3], v[2:3], v[230:231]
	v_pk_mul_f32 v[4:5], v[4:5], v[232:233]
	v_pk_mul_f32 v[6:7], v[6:7], v[234:235]
	v_pk_mul_f32 v[8:9], v[8:9], v[236:237]
	v_pk_mul_f32 v[10:11], v[10:11], v[238:239]
	v_pk_mul_f32 v[12:13], v[12:13], v[240:241]
	v_pk_mul_f32 v[14:15], v[14:15], v[242:243]
	v_pk_mul_f32 v[48:49], v[48:49], v[228:229]
	v_pk_mul_f32 v[50:51], v[50:51], v[230:231]
	v_pk_mul_f32 v[52:53], v[52:53], v[232:233]
	v_pk_mul_f32 v[54:55], v[54:55], v[234:235]
	v_pk_mul_f32 v[56:57], v[56:57], v[236:237]
	v_pk_mul_f32 v[58:59], v[58:59], v[238:239]
	v_pk_mul_f32 v[60:61], v[60:61], v[240:241]
	v_pk_mul_f32 v[62:63], v[62:63], v[242:243]
	v_pk_mul_f32 v[32:33], v[32:33], v[228:229]
	v_pk_mul_f32 v[34:35], v[34:35], v[230:231]
	v_pk_mul_f32 v[36:37], v[36:37], v[232:233]
	v_pk_mul_f32 v[38:39], v[38:39], v[234:235]
	v_pk_mul_f32 v[40:41], v[40:41], v[236:237]
	v_pk_mul_f32 v[42:43], v[42:43], v[238:239]
	v_pk_mul_f32 v[44:45], v[44:45], v[240:241]
	v_pk_mul_f32 v[46:47], v[46:47], v[242:243]
	v_pk_mul_f32 v[16:17], v[16:17], v[228:229]
	v_pk_mul_f32 v[18:19], v[18:19], v[230:231]
	v_pk_mul_f32 v[20:21], v[20:21], v[232:233]
	v_pk_mul_f32 v[22:23], v[22:23], v[234:235]
	v_pk_mul_f32 v[24:25], v[24:25], v[236:237]
	v_pk_mul_f32 v[26:27], v[26:27], v[238:239]
	v_pk_mul_f32 v[28:29], v[28:29], v[240:241]
	v_pk_mul_f32 v[30:31], v[30:31], v[242:243]

; __device__ __forceinline__ void partialSM(f32x16& p0, f32x16& p1, float& m_reg, float& mn, float& alpha) {
;     ...
;   for (int r = 0; r < 16; ++r) p0[r] = __builtin_amdgcn_exp2f(p0[r]);
; }
; __device__ __forceinline__ void finishSM(f32x16& p0, f32x16& p1, float alpha, float& l_reg, bf16x8& pa0, bf16x8& pa1, bf16x8& pa2, bf16x8& pa3) {
; #pragma unroll
;   for (int r = 0; r < 16; ++r) p1[r] = __builtin_amdgcn_exp2f(p1[r]);
;   float ps = 0;
; #pragma unroll
;   for (int r = 0; r < 16; ++r) ps += p0[r];
; #pragma unroll
;   for (int r = 0; r < 16; ++r) ps += p1[r];
;   { auto rr = __builtin_amdgcn_permlane32_swap(__float_as_uint(ps), __float_as_uint(ps), false, false);
;     ps = __uint_as_float(rr[0]) + __uint_as_float(rr[1]); }
;   l_reg = l_reg * alpha + ps;
;     ...
;   PK4(p0, 0, pa0); PK4(p0, 8, pa1); PK4(p1, 0, pa2); PK4(p1, 8, pa3);
;     ...
; }
.Lda_noresc_3:
	v_exp_f32_e32 v80, v80
	v_exp_f32_e32 v81, v81
	v_exp_f32_e32 v82, v82
	v_exp_f32_e32 v83, v83
	v_exp_f32_e32 v84, v84
	v_exp_f32_e32 v85, v85
	v_exp_f32_e32 v86, v86
	v_exp_f32_e32 v87, v87
	v_exp_f32_e32 v88, v88
	v_exp_f32_e32 v89, v89
	v_exp_f32_e32 v90, v90
	v_exp_f32_e32 v91, v91
	v_exp_f32_e32 v92, v92
	v_exp_f32_e32 v93, v93
	v_exp_f32_e32 v94, v94
	v_exp_f32_e32 v95, v95
	v_exp_f32_e32 v64, v64
	v_exp_f32_e32 v65, v65
	v_exp_f32_e32 v66, v66
	v_exp_f32_e32 v67, v67
	v_exp_f32_e32 v68, v68
	v_exp_f32_e32 v69, v69
	v_exp_f32_e32 v70, v70
	v_exp_f32_e32 v71, v71
	v_exp_f32_e32 v72, v72
	v_exp_f32_e32 v73, v73
	v_exp_f32_e32 v74, v74
	v_exp_f32_e32 v75, v75
	v_exp_f32_e32 v76, v76
	v_exp_f32_e32 v77, v77
	v_exp_f32_e32 v78, v78
	v_exp_f32_e32 v79, v79
	v_add_f32_e32 v190, v80, v81
	v_add_f32_e32 v191, v82, v83
	v_add_f32_e32 v190, v190, v84
	v_add_f32_e32 v191, v191, v85
	v_add_f32_e32 v190, v190, v86
	v_add_f32_e32 v191, v191, v87
	v_add_f32_e32 v190, v190, v88
	v_add_f32_e32 v191, v191, v89
	v_add_f32_e32 v190, v190, v90
	v_add_f32_e32 v191, v191, v91
	v_add_f32_e32 v190, v190, v92
	v_add_f32_e32 v191, v191, v93
	v_add_f32_e32 v190, v190, v94
	v_add_f32_e32 v191, v191, v95
	v_add_f32_e32 v190, v190, v64
	v_add_f32_e32 v191, v191, v65
	v_add_f32_e32 v190, v190, v66
	v_add_f32_e32 v191, v191, v67
	v_add_f32_e32 v190, v190, v68
	v_add_f32_e32 v191, v191, v69
	v_add_f32_e32 v190, v190, v70
	v_add_f32_e32 v191, v191, v71
	v_add_f32_e32 v190, v190, v72
	v_add_f32_e32 v191, v191, v73
	v_add_f32_e32 v190, v190, v74
	v_add_f32_e32 v191, v191, v75
	v_add_f32_e32 v190, v190, v76
	v_add_f32_e32 v191, v191, v77
	v_add_f32_e32 v190, v190, v78
	v_add_f32_e32 v191, v191, v79
	v_add_f32_e32 v190, v190, v191
	v_mov_b32_e32 v191, v190
	v_cvt_pk_bf16_f32 v166, v80, v81
	v_cvt_pk_bf16_f32 v167, v82, v83
	v_cvt_pk_bf16_f32 v168, v84, v85
	v_cvt_pk_bf16_f32 v169, v86, v87
	v_cvt_pk_bf16_f32 v170, v88, v89
	v_cvt_pk_bf16_f32 v171, v90, v91
	v_cvt_pk_bf16_f32 v172, v92, v93
	v_cvt_pk_bf16_f32 v173, v94, v95
	v_cvt_pk_bf16_f32 v176, v64, v65
	v_cvt_pk_bf16_f32 v177, v66, v67
	v_cvt_pk_bf16_f32 v178, v68, v69
	v_cvt_pk_bf16_f32 v179, v70, v71
	v_cvt_pk_bf16_f32 v180, v72, v73
	v_cvt_pk_bf16_f32 v181, v74, v75
	v_cvt_pk_bf16_f32 v182, v76, v77
	v_cvt_pk_bf16_f32 v183, v78, v79
	s_nop 1
	v_permlane32_swap_b32_e32 v190, v191
	v_permlane32_swap_b32_e32 v166, v168
	v_permlane32_swap_b32_e32 v167, v169
	v_permlane32_swap_b32_e32 v170, v172
	v_permlane32_swap_b32_e32 v171, v173
	v_permlane32_swap_b32_e32 v176, v178
	v_permlane32_swap_b32_e32 v177, v179
	v_permlane32_swap_b32_e32 v180, v182
	v_permlane32_swap_b32_e32 v181, v183
	v_add_f32_e32 v190, v190, v191
	v_add_f32_e32 v175, v175, v190
	s_add_u32 s31, s31, 1
	s_cmp_lt_u32 s31, 132
	s_cbranch_scc0 .Lda_skipk_3
	ds_read_b128 v[150:153], v204 offset:0
	ds_read_b128 v[154:157], v204 offset:8192
	ds_read_b128 v[158:161], v205 offset:0
	ds_read_b128 v[162:165], v205 offset:8192
	ds_read_b128 v[228:231], v206 offset:0
	ds_read_b128 v[232:235], v206 offset:8192
	ds_read_b128 v[236:239], v207 offset:0
	ds_read_b128 v[240:243], v207 offset:8192
